# v9 + GEMM per-tile trims: accumulator zeroing with 64-bit moves (14 GEMM instances), removed redundant self-canonicalizing v_max before relu in FFN-up epilogues (store-data hazards re-padded)
# speedup vs baseline: 1.0091x; 1.0040x over previous
;     __device__ __forceinline__ bool next(int i, Unit& u) const { const int L = i * G + c; if (L >= nunits) return false; const int t = L / S, ks = L % S; u.pm = pm0 + t / nN; u.pn = t % nN; u.ko = ks * Ksub; return true; }
; template <class Epi, class Sched, bool ALIGN_EPI = false, bool SP2 = false>
; __device__ __forceinline__ void gemm_phase(PG8_LAS unsigned char* lds, const Gemm g, const Sched& S, const Epi& E) {
;     ...
;         const bool has_next = S.next(ui + 1, nxt);
;         const char* nA = has_next ? (const char*)g.A + (size_t)nxt.pm * tstep + (size_t)nxt.ko * 2 : cA; const char* nB = has_next ? (const char*)g.Bt + (size_t)nxt.pn * tstep + (size_t)nxt.ko * 2 : cB;
;     ...
; #pragma unroll
;         for (int a = 0; a < 2; ++a)
; #pragma unroll
;             for (int b = 0; b < 2; ++b)
; #pragma unroll
;                 for (int m = 0; m < 4; ++m)
; #pragma unroll
;                     for (int n = 0; n < 2; ++n) acc[a][b][m][n] = (f32x4){0.f, 0.f, 0.f, 0.f};
.LBB0_189:
	s_ashr_i32 s25, s24, 31
	s_lshl_b64 s[26:27], s[24:25], 19
	s_add_u32 s26, s68, s26
	s_addc_u32 s27, s69, s27
	s_and_b64 s[28:29], s[4:5], exec
	s_cselect_b32 s25, s27, s31
	s_cselect_b32 s43, s26, s30
	s_ashr_i32 s23, s22, 31
	s_lshl_b64 s[28:29], s[22:23], 19
	s_add_u32 s28, s0, s28
	s_addc_u32 s29, s1, s29
	s_and_b64 s[36:37], s[4:5], exec
	s_cselect_b32 s23, s29, s35
	s_cselect_b32 s44, s28, s34
	s_add_u32 s30, s30, 0x40080
	s_addc_u32 s31, s31, 0
	s_add_u32 s45, s34, 0x100
	v_mov_b32_e32 v2, 0
	s_addc_u32 s46, s35, 0
	s_mov_b32 s47, -2
	v_mov_b32_e32 v3, v2
	v_mov_b64_e32 v[4:5], 0
	v_mov_b64_e32 v[6:7], 0
	v_mov_b64_e32 v[8:9], 0
	v_mov_b64_e32 v[10:11], 0
	v_mov_b64_e32 v[12:13], 0
	v_mov_b64_e32 v[14:15], 0
	v_mov_b64_e32 v[16:17], 0
	v_mov_b64_e32 v[18:19], 0
	v_mov_b64_e32 v[20:21], 0
	v_mov_b64_e32 v[22:23], 0
	v_mov_b64_e32 v[24:25], 0
	v_mov_b64_e32 v[26:27], 0
	v_mov_b64_e32 v[28:29], 0
	v_mov_b64_e32 v[30:31], 0
	v_mov_b64_e32 v[32:33], 0
	v_mov_b64_e32 v[34:35], 0
	v_mov_b64_e32 v[36:37], 0
	v_mov_b64_e32 v[38:39], 0
	v_mov_b64_e32 v[40:41], 0
	v_mov_b64_e32 v[42:43], 0
	v_mov_b64_e32 v[44:45], 0
	v_mov_b64_e32 v[46:47], 0
	v_mov_b64_e32 v[48:49], 0
	v_mov_b64_e32 v[50:51], 0
	v_mov_b64_e32 v[52:53], 0
	v_mov_b64_e32 v[54:55], 0
	v_mov_b64_e32 v[56:57], 0
	v_mov_b64_e32 v[58:59], 0
	v_mov_b64_e32 v[60:61], 0
	v_mov_b64_e32 v[62:63], 0
	v_mov_b64_e32 v[64:65], 0
	v_mov_b64_e32 v[66:67], 0
	v_mov_b64_e32 v[68:69], 0
	v_mov_b64_e32 v[70:71], 0
	v_mov_b64_e32 v[72:73], 0
	v_mov_b64_e32 v[74:75], 0
	v_mov_b64_e32 v[76:77], 0
	v_mov_b64_e32 v[78:79], 0
	v_mov_b64_e32 v[80:81], 0
	v_mov_b64_e32 v[82:83], 0
	v_mov_b64_e32 v[84:85], 0
	v_mov_b64_e32 v[86:87], 0
	v_mov_b64_e32 v[88:89], 0
	v_mov_b64_e32 v[90:91], 0
	v_mov_b64_e32 v[92:93], 0
	v_mov_b64_e32 v[94:95], 0
	v_mov_b64_e32 v[96:97], 0
	v_mov_b64_e32 v[98:99], 0
	v_mov_b64_e32 v[100:101], 0
	v_mov_b64_e32 v[102:103], 0
	v_mov_b64_e32 v[104:105], 0
	v_mov_b64_e32 v[106:107], 0
	v_mov_b64_e32 v[108:109], 0
	v_mov_b64_e32 v[110:111], 0
	v_mov_b64_e32 v[112:113], 0
	v_mov_b64_e32 v[114:115], 0
	v_mov_b64_e32 v[116:117], 0
	v_mov_b64_e32 v[118:119], 0
	v_mov_b64_e32 v[120:121], 0
	v_mov_b64_e32 v[122:123], 0
	v_mov_b64_e32 v[124:125], 0
	v_mov_b64_e32 v[126:127], 0
	v_mov_b64_e32 v[128:129], 0

; template <class Epi, class Sched, bool ALIGN_EPI = false, bool SP2 = false>
; __device__ __forceinline__ void gemm_phase(PG8_LAS unsigned char* lds, const Gemm g, const Sched& S, const Epi& E) {
;     ...
; #pragma unroll
;         for (int a = 0; a < 2; ++a)
; #pragma unroll
;             for (int b = 0; b < 2; ++b)
; #pragma unroll
;                 for (int m = 0; m < 4; ++m)
; #pragma unroll
;                     for (int n = 0; n < 2; ++n) acc[a][b][m][n] = (f32x4){0.f, 0.f, 0.f, 0.f};
.LBB0_373:
	s_add_u32 s24, s24, 0x30080
	s_addc_u32 s25, s25, 0
	s_add_u32 s42, s28, 0x100
	v_mov_b32_e32 v2, 0
	s_addc_u32 s43, s29, 0
	s_mov_b32 s44, -2
	v_mov_b32_e32 v3, v2
	v_mov_b64_e32 v[4:5], 0
	v_mov_b64_e32 v[6:7], 0
	v_mov_b64_e32 v[8:9], 0
	v_mov_b64_e32 v[10:11], 0
	v_mov_b64_e32 v[12:13], 0
	v_mov_b64_e32 v[14:15], 0
	v_mov_b64_e32 v[16:17], 0
	v_mov_b64_e32 v[18:19], 0
	v_mov_b64_e32 v[20:21], 0
	v_mov_b64_e32 v[22:23], 0
	v_mov_b64_e32 v[24:25], 0
	v_mov_b64_e32 v[26:27], 0
	v_mov_b64_e32 v[28:29], 0
	v_mov_b64_e32 v[30:31], 0
	v_mov_b64_e32 v[32:33], 0
	v_mov_b64_e32 v[34:35], 0
	v_mov_b64_e32 v[36:37], 0
	v_mov_b64_e32 v[38:39], 0
	v_mov_b64_e32 v[40:41], 0
	v_mov_b64_e32 v[42:43], 0
	v_mov_b64_e32 v[44:45], 0
	v_mov_b64_e32 v[46:47], 0
	v_mov_b64_e32 v[48:49], 0
	v_mov_b64_e32 v[50:51], 0
	v_mov_b64_e32 v[52:53], 0
	v_mov_b64_e32 v[54:55], 0
	v_mov_b64_e32 v[56:57], 0
	v_mov_b64_e32 v[58:59], 0
	v_mov_b64_e32 v[60:61], 0
	v_mov_b64_e32 v[62:63], 0
	v_mov_b64_e32 v[64:65], 0
	v_mov_b64_e32 v[66:67], 0
	v_mov_b64_e32 v[68:69], 0
	v_mov_b64_e32 v[70:71], 0
	v_mov_b64_e32 v[72:73], 0
	v_mov_b64_e32 v[74:75], 0
	v_mov_b64_e32 v[76:77], 0
	v_mov_b64_e32 v[78:79], 0
	v_mov_b64_e32 v[80:81], 0
	v_mov_b64_e32 v[82:83], 0
	v_mov_b64_e32 v[84:85], 0
	v_mov_b64_e32 v[86:87], 0
	v_mov_b64_e32 v[88:89], 0
	v_mov_b64_e32 v[90:91], 0
	v_mov_b64_e32 v[92:93], 0
	v_mov_b64_e32 v[94:95], 0
	v_mov_b64_e32 v[96:97], 0
	v_mov_b64_e32 v[98:99], 0
	v_mov_b64_e32 v[100:101], 0
	v_mov_b64_e32 v[102:103], 0
	v_mov_b64_e32 v[104:105], 0
	v_mov_b64_e32 v[106:107], 0
	v_mov_b64_e32 v[108:109], 0
	v_mov_b64_e32 v[110:111], 0
	v_mov_b64_e32 v[112:113], 0
	v_mov_b64_e32 v[114:115], 0
	v_mov_b64_e32 v[116:117], 0
	v_mov_b64_e32 v[118:119], 0
	v_mov_b64_e32 v[120:121], 0
	v_mov_b64_e32 v[122:123], 0
	v_mov_b64_e32 v[124:125], 0
	v_mov_b64_e32 v[126:127], 0
	v_mov_b64_e32 v[128:129], 0

;     __device__ __forceinline__ bool next(int i, Unit& u) const { const int L = i * G + c; if (L >= nunits) return false; const int t = L / S, ks = L % S; u.pm = pm0 + t / nN; u.pn = t % nN; u.ko = ks * Ksub; return true; }
; template <class Epi, class Sched, bool ALIGN_EPI = false, bool SP2 = false>
; __device__ __forceinline__ void gemm_phase(PG8_LAS unsigned char* lds, const Gemm g, const Sched& S, const Epi& E) {
;     ...
;         const bool has_next = S.next(ui + 1, nxt);
;         const char* nA = has_next ? (const char*)g.A + (size_t)nxt.pm * tstep + (size_t)nxt.ko * 2 : cA; const char* nB = has_next ? (const char*)g.Bt + (size_t)nxt.pn * tstep + (size_t)nxt.ko * 2 : cB;
;     ...
; #pragma unroll
;         for (int a = 0; a < 2; ++a)
; #pragma unroll
;             for (int b = 0; b < 2; ++b)
; #pragma unroll
;                 for (int m = 0; m < 4; ++m)
; #pragma unroll
;                     for (int n = 0; n < 2; ++n) acc[a][b][m][n] = (f32x4){0.f, 0.f, 0.f, 0.f};
.LBB0_389:
	s_ashr_i32 s25, s24, 31
	s_lshl_b64 s[30:31], s[24:25], 17
	s_add_u32 s30, s70, s30
	s_addc_u32 s31, s71, s31
	s_and_b64 s[34:35], s[4:5], exec
	s_cselect_b32 s25, s31, s29
	s_cselect_b32 s56, s30, s28
	s_ashr_i32 s23, s22, 31
	s_lshl_b64 s[34:35], s[22:23], 17
	s_add_u32 s34, s80, s34
	s_addc_u32 s35, s81, s35
	s_and_b64 s[36:37], s[4:5], exec
	v_mov_b32_e32 v2, 0
	s_cselect_b32 s23, s35, s21
	s_cselect_b32 s57, s34, s20
	s_mov_b32 s40, 0
	s_mov_b64 s[36:37], -1
	s_mov_b64 s[38:39], 0
	v_mov_b32_e32 v3, v2
	v_mov_b64_e32 v[4:5], 0
	v_mov_b64_e32 v[6:7], 0
	v_mov_b64_e32 v[8:9], 0
	v_mov_b64_e32 v[10:11], 0
	v_mov_b64_e32 v[12:13], 0
	v_mov_b64_e32 v[14:15], 0
	v_mov_b64_e32 v[16:17], 0
	v_mov_b64_e32 v[18:19], 0
	v_mov_b64_e32 v[20:21], 0
	v_mov_b64_e32 v[22:23], 0
	v_mov_b64_e32 v[24:25], 0
	v_mov_b64_e32 v[26:27], 0
	v_mov_b64_e32 v[28:29], 0
	v_mov_b64_e32 v[30:31], 0
	v_mov_b64_e32 v[32:33], 0
	v_mov_b64_e32 v[34:35], 0
	v_mov_b64_e32 v[36:37], 0
	v_mov_b64_e32 v[38:39], 0
	v_mov_b64_e32 v[40:41], 0
	v_mov_b64_e32 v[42:43], 0
	v_mov_b64_e32 v[44:45], 0
	v_mov_b64_e32 v[46:47], 0
	v_mov_b64_e32 v[48:49], 0
	v_mov_b64_e32 v[50:51], 0
	v_mov_b64_e32 v[52:53], 0
	v_mov_b64_e32 v[54:55], 0
	v_mov_b64_e32 v[56:57], 0
	v_mov_b64_e32 v[58:59], 0
	v_mov_b64_e32 v[60:61], 0
	v_mov_b64_e32 v[62:63], 0
	v_mov_b64_e32 v[64:65], 0
	v_mov_b64_e32 v[66:67], 0
	v_mov_b64_e32 v[68:69], 0
	v_mov_b64_e32 v[70:71], 0
	v_mov_b64_e32 v[72:73], 0
	v_mov_b64_e32 v[74:75], 0
	v_mov_b64_e32 v[76:77], 0
	v_mov_b64_e32 v[78:79], 0
	v_mov_b64_e32 v[80:81], 0
	v_mov_b64_e32 v[82:83], 0
	v_mov_b64_e32 v[84:85], 0
	v_mov_b64_e32 v[86:87], 0
	v_mov_b64_e32 v[88:89], 0
	v_mov_b64_e32 v[90:91], 0
	v_mov_b64_e32 v[92:93], 0
	v_mov_b64_e32 v[94:95], 0
	v_mov_b64_e32 v[96:97], 0
	v_mov_b64_e32 v[98:99], 0
	v_mov_b64_e32 v[100:101], 0
	v_mov_b64_e32 v[102:103], 0
	v_mov_b64_e32 v[104:105], 0
	v_mov_b64_e32 v[106:107], 0
	v_mov_b64_e32 v[108:109], 0
	v_mov_b64_e32 v[110:111], 0
	v_mov_b64_e32 v[112:113], 0
	v_mov_b64_e32 v[114:115], 0
	v_mov_b64_e32 v[116:117], 0
	v_mov_b64_e32 v[118:119], 0
	v_mov_b64_e32 v[120:121], 0
	v_mov_b64_e32 v[122:123], 0
	v_mov_b64_e32 v[124:125], 0
	v_mov_b64_e32 v[126:127], 0
	v_mov_b64_e32 v[128:129], 0

;     __device__ __forceinline__ bool next(int i, Unit& u) const { const int L = i * G + c; if (L >= nunits) return false; const int t = L / S, ks = L % S; u.pm = pm0 + t / nN; u.pn = t % nN; u.ko = ks * Ksub; return true; }
; template <class Epi, class Sched, bool ALIGN_EPI = false, bool SP2 = false>
; __device__ __forceinline__ void gemm_phase(PG8_LAS unsigned char* lds, const Gemm g, const Sched& S, const Epi& E) {
;     ...
;         const bool has_next = S.next(ui + 1, nxt);
;         const char* nA = has_next ? (const char*)g.A + (size_t)nxt.pm * tstep + (size_t)nxt.ko * 2 : cA; const char* nB = has_next ? (const char*)g.Bt + (size_t)nxt.pn * tstep + (size_t)nxt.ko * 2 : cB;
;     ...
; #pragma unroll
;         for (int a = 0; a < 2; ++a)
; #pragma unroll
;             for (int b = 0; b < 2; ++b)
; #pragma unroll
;                 for (int m = 0; m < 4; ++m)
; #pragma unroll
;                     for (int n = 0; n < 2; ++n) acc[a][b][m][n] = (f32x4){0.f, 0.f, 0.f, 0.f};
.LBB0_826:
	s_ashr_i32 s17, s16, 31
	s_lshl_b64 s[18:19], s[16:17], 19
	s_add_u32 s18, s68, s18
	s_addc_u32 s19, s69, s19
	s_and_b64 s[26:27], s[4:5], exec
	s_cselect_b32 s17, s19, s23
	s_cselect_b32 s40, s18, s22
	s_ashr_i32 s15, s14, 31
	s_lshl_b64 s[26:27], s[14:15], 19
	s_add_u32 s26, s56, s26
	s_addc_u32 s27, s57, s27
	s_and_b64 s[28:29], s[4:5], exec
	s_cselect_b32 s15, s27, s25
	s_cselect_b32 s41, s26, s24
	s_add_u32 s22, s22, 0x40080
	s_addc_u32 s23, s23, 0
	s_add_u32 s42, s24, 0x100
	v_mov_b32_e32 v2, 0
	s_addc_u32 s43, s25, 0
	s_mov_b32 s44, -2
	v_mov_b32_e32 v3, v2
	v_mov_b64_e32 v[4:5], 0
	v_mov_b64_e32 v[6:7], 0
	v_mov_b64_e32 v[8:9], 0
	v_mov_b64_e32 v[10:11], 0
	v_mov_b64_e32 v[12:13], 0
	v_mov_b64_e32 v[14:15], 0
	v_mov_b64_e32 v[16:17], 0
	v_mov_b64_e32 v[18:19], 0
	v_mov_b64_e32 v[20:21], 0
	v_mov_b64_e32 v[22:23], 0
	v_mov_b64_e32 v[24:25], 0
	v_mov_b64_e32 v[26:27], 0
	v_mov_b64_e32 v[28:29], 0
	v_mov_b64_e32 v[30:31], 0
	v_mov_b64_e32 v[32:33], 0
	v_mov_b64_e32 v[34:35], 0
	v_mov_b64_e32 v[36:37], 0
	v_mov_b64_e32 v[38:39], 0
	v_mov_b64_e32 v[40:41], 0
	v_mov_b64_e32 v[42:43], 0
	v_mov_b64_e32 v[44:45], 0
	v_mov_b64_e32 v[46:47], 0
	v_mov_b64_e32 v[48:49], 0
	v_mov_b64_e32 v[50:51], 0
	v_mov_b64_e32 v[52:53], 0
	v_mov_b64_e32 v[54:55], 0
	v_mov_b64_e32 v[56:57], 0
	v_mov_b64_e32 v[58:59], 0
	v_mov_b64_e32 v[60:61], 0
	v_mov_b64_e32 v[62:63], 0
	v_mov_b64_e32 v[64:65], 0
	v_mov_b64_e32 v[66:67], 0
	v_mov_b64_e32 v[68:69], 0
	v_mov_b64_e32 v[70:71], 0
	v_mov_b64_e32 v[72:73], 0
	v_mov_b64_e32 v[74:75], 0
	v_mov_b64_e32 v[76:77], 0
	v_mov_b64_e32 v[78:79], 0
	v_mov_b64_e32 v[80:81], 0
	v_mov_b64_e32 v[82:83], 0
	v_mov_b64_e32 v[84:85], 0
	v_mov_b64_e32 v[86:87], 0
	v_mov_b64_e32 v[88:89], 0
	v_mov_b64_e32 v[90:91], 0
	v_mov_b64_e32 v[92:93], 0
	v_mov_b64_e32 v[94:95], 0
	v_mov_b64_e32 v[96:97], 0
	v_mov_b64_e32 v[98:99], 0
	v_mov_b64_e32 v[100:101], 0
	v_mov_b64_e32 v[102:103], 0
	v_mov_b64_e32 v[104:105], 0
	v_mov_b64_e32 v[106:107], 0
	v_mov_b64_e32 v[108:109], 0
	v_mov_b64_e32 v[110:111], 0
	v_mov_b64_e32 v[112:113], 0
	v_mov_b64_e32 v[114:115], 0
	v_mov_b64_e32 v[116:117], 0
	v_mov_b64_e32 v[118:119], 0
	v_mov_b64_e32 v[120:121], 0
	v_mov_b64_e32 v[122:123], 0
	v_mov_b64_e32 v[124:125], 0
	v_mov_b64_e32 v[126:127], 0
	v_mov_b64_e32 v[128:129], 0

; template <class Epi, class Sched, bool ALIGN_EPI = false, bool SP2 = false>
; __device__ __forceinline__ void gemm_phase(PG8_LAS unsigned char* lds, const Gemm g, const Sched& S, const Epi& E) {
;     ...
; #pragma unroll
;         for (int a = 0; a < 2; ++a)
; #pragma unroll
;             for (int b = 0; b < 2; ++b)
; #pragma unroll
;                 for (int m = 0; m < 4; ++m)
; #pragma unroll
;                     for (int n = 0; n < 2; ++n) acc[a][b][m][n] = (f32x4){0.f, 0.f, 0.f, 0.f};
.LBB0_846:
	v_mov_b32_e32 v2, 0
	s_mov_b32 s7, 0
	s_mov_b64 s[34:35], -1
	s_mov_b64 s[36:37], 0
	v_mov_b32_e32 v3, v2
	v_mov_b64_e32 v[4:5], 0
	v_mov_b64_e32 v[6:7], 0
	v_mov_b64_e32 v[8:9], 0
	v_mov_b64_e32 v[10:11], 0
	v_mov_b64_e32 v[12:13], 0
	v_mov_b64_e32 v[14:15], 0
	v_mov_b64_e32 v[16:17], 0
	v_mov_b64_e32 v[18:19], 0
	v_mov_b64_e32 v[20:21], 0
	v_mov_b64_e32 v[22:23], 0
	v_mov_b64_e32 v[24:25], 0
	v_mov_b64_e32 v[26:27], 0
	v_mov_b64_e32 v[28:29], 0
	v_mov_b64_e32 v[30:31], 0
	v_mov_b64_e32 v[32:33], 0
	v_mov_b64_e32 v[34:35], 0
	v_mov_b64_e32 v[36:37], 0
	v_mov_b64_e32 v[38:39], 0
	v_mov_b64_e32 v[40:41], 0
	v_mov_b64_e32 v[42:43], 0
	v_mov_b64_e32 v[44:45], 0
	v_mov_b64_e32 v[46:47], 0
	v_mov_b64_e32 v[48:49], 0
	v_mov_b64_e32 v[50:51], 0
	v_mov_b64_e32 v[52:53], 0
	v_mov_b64_e32 v[54:55], 0
	v_mov_b64_e32 v[56:57], 0
	v_mov_b64_e32 v[58:59], 0
	v_mov_b64_e32 v[60:61], 0
	v_mov_b64_e32 v[62:63], 0
	v_mov_b64_e32 v[64:65], 0
	v_mov_b64_e32 v[66:67], 0
	v_mov_b64_e32 v[68:69], 0
	v_mov_b64_e32 v[70:71], 0
	v_mov_b64_e32 v[72:73], 0
	v_mov_b64_e32 v[74:75], 0
	v_mov_b64_e32 v[76:77], 0
	v_mov_b64_e32 v[78:79], 0
	v_mov_b64_e32 v[80:81], 0
	v_mov_b64_e32 v[82:83], 0
	v_mov_b64_e32 v[84:85], 0
	v_mov_b64_e32 v[86:87], 0
	v_mov_b64_e32 v[88:89], 0
	v_mov_b64_e32 v[90:91], 0
	v_mov_b64_e32 v[92:93], 0
	v_mov_b64_e32 v[94:95], 0
	v_mov_b64_e32 v[96:97], 0
	v_mov_b64_e32 v[98:99], 0
	v_mov_b64_e32 v[100:101], 0
	v_mov_b64_e32 v[102:103], 0
	v_mov_b64_e32 v[104:105], 0
	v_mov_b64_e32 v[106:107], 0
	v_mov_b64_e32 v[108:109], 0
	v_mov_b64_e32 v[110:111], 0
	v_mov_b64_e32 v[112:113], 0
	v_mov_b64_e32 v[114:115], 0
	v_mov_b64_e32 v[116:117], 0
	v_mov_b64_e32 v[118:119], 0
	v_mov_b64_e32 v[120:121], 0
	v_mov_b64_e32 v[122:123], 0
	v_mov_b64_e32 v[124:125], 0
	v_mov_b64_e32 v[126:127], 0
	v_mov_b64_e32 v[128:129], 0

;     __device__ __forceinline__ bool next(int i, Unit& u) const { const int L = i * G + c; if (L >= nunits) return false; const int t = L / S, ks = L % S; u.pm = pm0 + t / nN; u.pn = t % nN; u.ko = ks * Ksub; return true; }
; template <class Epi, class Sched, bool ALIGN_EPI = false, bool SP2 = false>
; __device__ __forceinline__ void gemm_phase(PG8_LAS unsigned char* lds, const Gemm g, const Sched& S, const Epi& E) {
;     ...
;         const bool has_next = S.next(ui + 1, nxt);
;         const char* nA = has_next ? (const char*)g.A + (size_t)nxt.pm * tstep + (size_t)nxt.ko * 2 : cA; const char* nB = has_next ? (const char*)g.Bt + (size_t)nxt.pn * tstep + (size_t)nxt.ko * 2 : cB;
;     ...
; #pragma unroll
;         for (int a = 0; a < 2; ++a)
; #pragma unroll
;             for (int b = 0; b < 2; ++b)
; #pragma unroll
;                 for (int m = 0; m < 4; ++m)
; #pragma unroll
;                     for (int n = 0; n < 2; ++n) acc[a][b][m][n] = (f32x4){0.f, 0.f, 0.f, 0.f};
.LBB0_1018:
	s_ashr_i32 s15, s14, 31
	s_lshl_b64 s[16:17], s[14:15], 19
	s_add_u32 s16, s68, s16
	s_addc_u32 s17, s69, s17
	s_and_b64 s[18:19], s[4:5], exec
	s_cselect_b32 s15, s17, s23
	s_cselect_b32 s40, s16, s22
	s_ashr_i32 s13, s12, 31
	s_lshl_b64 s[18:19], s[12:13], 19
	s_add_u32 s18, s65, s18
	s_addc_u32 s19, s66, s19
	s_and_b64 s[26:27], s[4:5], exec
	s_cselect_b32 s13, s19, s25
	s_cselect_b32 s41, s18, s24
	s_add_u32 s22, s22, 0x40080
	s_addc_u32 s23, s23, 0
	s_add_u32 s42, s24, 0x100
	v_mov_b32_e32 v2, 0
	s_addc_u32 s43, s25, 0
	s_mov_b32 s44, -2
	v_mov_b32_e32 v3, v2
	v_mov_b64_e32 v[4:5], 0
	v_mov_b64_e32 v[6:7], 0
	v_mov_b64_e32 v[8:9], 0
	v_mov_b64_e32 v[10:11], 0
	v_mov_b64_e32 v[12:13], 0
	v_mov_b64_e32 v[14:15], 0
	v_mov_b64_e32 v[16:17], 0
	v_mov_b64_e32 v[18:19], 0
	v_mov_b64_e32 v[20:21], 0
	v_mov_b64_e32 v[22:23], 0
	v_mov_b64_e32 v[24:25], 0
	v_mov_b64_e32 v[26:27], 0
	v_mov_b64_e32 v[28:29], 0
	v_mov_b64_e32 v[30:31], 0
	v_mov_b64_e32 v[32:33], 0
	v_mov_b64_e32 v[34:35], 0
	v_mov_b64_e32 v[36:37], 0
	v_mov_b64_e32 v[38:39], 0
	v_mov_b64_e32 v[40:41], 0
	v_mov_b64_e32 v[42:43], 0
	v_mov_b64_e32 v[44:45], 0
	v_mov_b64_e32 v[46:47], 0
	v_mov_b64_e32 v[48:49], 0
	v_mov_b64_e32 v[50:51], 0
	v_mov_b64_e32 v[52:53], 0
	v_mov_b64_e32 v[54:55], 0
	v_mov_b64_e32 v[56:57], 0
	v_mov_b64_e32 v[58:59], 0
	v_mov_b64_e32 v[60:61], 0
	v_mov_b64_e32 v[62:63], 0
	v_mov_b64_e32 v[64:65], 0
	v_mov_b64_e32 v[66:67], 0
	v_mov_b64_e32 v[68:69], 0
	v_mov_b64_e32 v[70:71], 0
	v_mov_b64_e32 v[72:73], 0
	v_mov_b64_e32 v[74:75], 0
	v_mov_b64_e32 v[76:77], 0
	v_mov_b64_e32 v[78:79], 0
	v_mov_b64_e32 v[80:81], 0
	v_mov_b64_e32 v[82:83], 0
	v_mov_b64_e32 v[84:85], 0
	v_mov_b64_e32 v[86:87], 0
	v_mov_b64_e32 v[88:89], 0
	v_mov_b64_e32 v[90:91], 0
	v_mov_b64_e32 v[92:93], 0
	v_mov_b64_e32 v[94:95], 0
	v_mov_b64_e32 v[96:97], 0
	v_mov_b64_e32 v[98:99], 0
	v_mov_b64_e32 v[100:101], 0
	v_mov_b64_e32 v[102:103], 0
	v_mov_b64_e32 v[104:105], 0
	v_mov_b64_e32 v[106:107], 0
	v_mov_b64_e32 v[108:109], 0
	v_mov_b64_e32 v[110:111], 0
	v_mov_b64_e32 v[112:113], 0
	v_mov_b64_e32 v[114:115], 0
	v_mov_b64_e32 v[116:117], 0
	v_mov_b64_e32 v[118:119], 0
	v_mov_b64_e32 v[120:121], 0
	v_mov_b64_e32 v[122:123], 0
	v_mov_b64_e32 v[124:125], 0
	v_mov_b64_e32 v[126:127], 0
	v_mov_b64_e32 v[128:129], 0

; __device__ __forceinline__ unsigned cvt_pk_bf16(float lo, float hi) { f32x2 v = {lo, hi}; bf16x2v b = __builtin_convertvector(v, bf16x2v); return __builtin_bit_cast(unsigned, b); }
;     __device__ __forceinline__ void operator()(const f32x4 (&acc)[2][2][4][2], const Unit& u, int wr, int wc, int fr, int fq) const {
;         const int row0 = u.pm * BM + wr * 64 + fr; const int col0 = u.pn * BM + wc * 32 + 8 * fq;
; #pragma unroll
;         for (int ai = 0; ai < 2; ++ai)
; #pragma unroll
;             for (int m = 0; m < 4; ++m) { bf16_t* rowp = O + (size_t)(row0 + ai * HALF + m * 16) * ldc + col0;
; #pragma unroll
;                 for (int bj = 0; bj < 2; ++bj) { f32x4 v0 = acc[ai][bj][m][0], v1 = acc[ai][bj][m][1];
;                     if (ACT == 2) {
; #pragma unroll
;                         for (int e = 0; e < 4; ++e) { float a = fmaxf(v0[e], 0.f), b = fmaxf(v1[e], 0.f); v0[e] = a * a; v1[e] = b * b; } }
;                     u32x4 w; w.x = cvt_pk_bf16(v0[0], v0[1]); w.y = cvt_pk_bf16(v0[2], v0[3]); w.z = cvt_pk_bf16(v1[0], v1[1]); w.w = cvt_pk_bf16(v1[2], v1[3]);
;                     *(u32x4*)(rowp + bj * HALF) = w; } }
.LBB0_1022:
	v_lshl_add_u32 v154, s20, 8, v1
	v_lshl_or_b32 v146, s39, 8, v148
	v_ashrrev_i32_e32 v155, 31, v154
	v_ashrrev_i32_e32 v147, 31, v146
	v_lshlrev_b64 v[156:157], 13, v[154:155]
	v_lshl_add_u64 v[156:157], s[62:63], 0, v[156:157]
	v_lshlrev_b64 v[158:159], 1, v[146:147]
	v_max_f32_e32 v122, 0, v122
	v_max_f32_e32 v123, 0, v123
	v_lshl_add_u64 v[146:147], v[156:157], 0, v[158:159]
	v_pk_mul_f32 v[156:157], v[122:123], v[122:123]
	v_max_f32_e32 v123, v124, v124
	v_max_f32_e32 v122, v128, v128
	v_max_f32_e32 v124, 0, v123
	v_max_f32_e32 v123, v129, v129
	v_max_f32_e32 v126, 0, v126
	v_max_f32_e32 v127, 0, v127
	v_max_f32_e32 v122, 0, v122
	v_max_f32_e32 v123, 0, v123
	v_max_f32_e32 v125, 0, v125
	v_pk_mul_f32 v[126:127], v[126:127], v[126:127]
	v_pk_mul_f32 v[128:129], v[122:123], v[122:123]
	v_pk_mul_f32 v[160:161], v[124:125], v[124:125]
	v_cvt_pk_bf16_f32 v122, v126, v127
	v_cvt_pk_bf16_f32 v123, v128, v129
	v_cvt_pk_bf16_f32 v124, v156, v157
	v_cvt_pk_bf16_f32 v125, v160, v161
	v_max_f32_e32 v114, 0, v114
	v_max_f32_e32 v115, 0, v115
	global_store_dwordx4 v[146:147], v[122:125], off
	s_nop 1
	v_pk_mul_f32 v[122:123], v[114:115], v[114:115]
	v_max_f32_e32 v115, v116, v116
	v_max_f32_e32 v114, v120, v120
	v_max_f32_e32 v116, 0, v115
	v_max_f32_e32 v115, v121, v121
	v_max_f32_e32 v118, 0, v118
	v_max_f32_e32 v119, 0, v119
	v_max_f32_e32 v114, 0, v114
	v_max_f32_e32 v115, 0, v115
	v_max_f32_e32 v117, 0, v117
	v_pk_mul_f32 v[118:119], v[118:119], v[118:119]
	v_pk_mul_f32 v[120:121], v[114:115], v[114:115]
	v_pk_mul_f32 v[124:125], v[116:117], v[116:117]
	v_cvt_pk_bf16_f32 v114, v118, v119
	v_cvt_pk_bf16_f32 v115, v120, v121
	v_cvt_pk_bf16_f32 v116, v122, v123
	v_cvt_pk_bf16_f32 v117, v124, v125
	v_max_f32_e32 v106, 0, v106
	v_max_f32_e32 v107, 0, v107
	global_store_dwordx4 v[146:147], v[114:117], off offset:256
	s_nop 1
	v_or_b32_e32 v114, 16, v154
	v_pk_mul_f32 v[116:117], v[106:107], v[106:107]
	v_max_f32_e32 v107, v108, v108
	v_ashrrev_i32_e32 v115, 31, v114
	v_max_f32_e32 v106, v112, v112
	v_max_f32_e32 v108, 0, v107
	v_max_f32_e32 v107, v113, v113
	v_lshlrev_b64 v[114:115], 13, v[114:115]
	v_max_f32_e32 v110, 0, v110
	v_max_f32_e32 v111, 0, v111
	v_max_f32_e32 v106, 0, v106
	v_max_f32_e32 v107, 0, v107
	v_max_f32_e32 v109, 0, v109
	v_lshl_add_u64 v[114:115], s[62:63], 0, v[114:115]
	v_pk_mul_f32 v[110:111], v[110:111], v[110:111]
	v_pk_mul_f32 v[112:113], v[106:107], v[106:107]
	v_pk_mul_f32 v[118:119], v[108:109], v[108:109]
	v_lshl_add_u64 v[114:115], v[114:115], 0, v[158:159]
	v_cvt_pk_bf16_f32 v106, v110, v111
	v_cvt_pk_bf16_f32 v107, v112, v113
	v_cvt_pk_bf16_f32 v108, v116, v117
	v_cvt_pk_bf16_f32 v109, v118, v119
	v_max_f32_e32 v98, 0, v98
	v_max_f32_e32 v99, 0, v99
	global_store_dwordx4 v[114:115], v[106:109], off
	s_nop 1
	v_pk_mul_f32 v[106:107], v[98:99], v[98:99]
	v_max_f32_e32 v99, v100, v100
	v_max_f32_e32 v98, v104, v104
	v_max_f32_e32 v100, 0, v99
	v_max_f32_e32 v99, v105, v105
	v_max_f32_e32 v102, 0, v102
	v_max_f32_e32 v103, 0, v103
	v_max_f32_e32 v98, 0, v98
	v_max_f32_e32 v99, 0, v99
	v_max_f32_e32 v101, 0, v101
	v_pk_mul_f32 v[102:103], v[102:103], v[102:103]
	v_pk_mul_f32 v[104:105], v[98:99], v[98:99]
	v_pk_mul_f32 v[108:109], v[100:101], v[100:101]
	v_cvt_pk_bf16_f32 v98, v102, v103
	v_cvt_pk_bf16_f32 v99, v104, v105
	v_cvt_pk_bf16_f32 v100, v106, v107
	v_cvt_pk_bf16_f32 v101, v108, v109
	v_max_f32_e32 v90, 0, v90
	v_max_f32_e32 v91, 0, v91
	global_store_dwordx4 v[114:115], v[98:101], off offset:256
	s_nop 1
	v_or_b32_e32 v98, 32, v154
	v_pk_mul_f32 v[100:101], v[90:91], v[90:91]
	v_max_f32_e32 v91, v92, v92
	v_ashrrev_i32_e32 v99, 31, v98
	v_max_f32_e32 v90, v96, v96
	v_max_f32_e32 v92, 0, v91
	v_max_f32_e32 v91, v97, v97
	v_lshlrev_b64 v[98:99], 13, v[98:99]
	v_max_f32_e32 v94, 0, v94
	v_max_f32_e32 v95, 0, v95
	v_max_f32_e32 v90, 0, v90
	v_max_f32_e32 v91, 0, v91
	v_max_f32_e32 v93, 0, v93
	v_lshl_add_u64 v[98:99], s[62:63], 0, v[98:99]
	v_pk_mul_f32 v[94:95], v[94:95], v[94:95]
	v_pk_mul_f32 v[96:97], v[90:91], v[90:91]
	v_pk_mul_f32 v[102:103], v[92:93], v[92:93]
	v_lshl_add_u64 v[98:99], v[98:99], 0, v[158:159]
	v_cvt_pk_bf16_f32 v90, v94, v95
	v_cvt_pk_bf16_f32 v91, v96, v97
	v_cvt_pk_bf16_f32 v92, v100, v101
	v_cvt_pk_bf16_f32 v93, v102, v103
	v_max_f32_e32 v82, 0, v82
	v_max_f32_e32 v83, 0, v83
	global_store_dwordx4 v[98:99], v[90:93], off
	s_nop 1
	v_pk_mul_f32 v[90:91], v[82:83], v[82:83]
	v_max_f32_e32 v83, v84, v84
	v_max_f32_e32 v82, v88, v88
	v_max_f32_e32 v84, 0, v83
	v_max_f32_e32 v83, v89, v89
	v_max_f32_e32 v86, 0, v86
	v_max_f32_e32 v87, 0, v87
	v_max_f32_e32 v82, 0, v82
	v_max_f32_e32 v83, 0, v83
	v_max_f32_e32 v85, 0, v85
	v_pk_mul_f32 v[86:87], v[86:87], v[86:87]
	v_pk_mul_f32 v[88:89], v[82:83], v[82:83]
	v_pk_mul_f32 v[92:93], v[84:85], v[84:85]
	v_cvt_pk_bf16_f32 v82, v86, v87
	v_cvt_pk_bf16_f32 v83, v88, v89
	v_cvt_pk_bf16_f32 v84, v90, v91
	v_cvt_pk_bf16_f32 v85, v92, v93
	v_max_f32_e32 v74, 0, v74
	v_max_f32_e32 v75, 0, v75
	global_store_dwordx4 v[98:99], v[82:85], off offset:256
	s_nop 1
	v_or_b32_e32 v82, 48, v154
	v_pk_mul_f32 v[84:85], v[74:75], v[74:75]
	v_max_f32_e32 v75, v76, v76
	v_ashrrev_i32_e32 v83, 31, v82
	v_max_f32_e32 v74, v80, v80
	v_max_f32_e32 v76, 0, v75
	v_max_f32_e32 v75, v81, v81
	v_lshlrev_b64 v[82:83], 13, v[82:83]
	v_max_f32_e32 v78, 0, v78
	v_max_f32_e32 v79, 0, v79
	v_max_f32_e32 v74, 0, v74
	v_max_f32_e32 v75, 0, v75
	v_max_f32_e32 v77, 0, v77
	v_lshl_add_u64 v[82:83], s[62:63], 0, v[82:83]
	v_pk_mul_f32 v[78:79], v[78:79], v[78:79]
	v_pk_mul_f32 v[80:81], v[74:75], v[74:75]
	v_pk_mul_f32 v[86:87], v[76:77], v[76:77]
	v_lshl_add_u64 v[82:83], v[82:83], 0, v[158:159]
; __device__ __forceinline__ unsigned cvt_pk_bf16(float lo, float hi) { f32x2 v = {lo, hi}; bf16x2v b = __builtin_convertvector(v, bf16x2v); return __builtin_bit_cast(unsigned, b); }
; #define PG8_BAR __builtin_amdgcn_s_barrier()
;     __device__ __forceinline__ void operator()(const f32x4 (&acc)[2][2][4][2], const Unit& u, int wr, int wc, int fr, int fq) const {
;         const int row0 = u.pm * BM + wr * 64 + fr; const int col0 = u.pn * BM + wc * 32 + 8 * fq;
; #pragma unroll
;         for (int ai = 0; ai < 2; ++ai)
; #pragma unroll
;             for (int m = 0; m < 4; ++m) { bf16_t* rowp = O + (size_t)(row0 + ai * HALF + m * 16) * ldc + col0;
; #pragma unroll
;                 for (int bj = 0; bj < 2; ++bj) { f32x4 v0 = acc[ai][bj][m][0], v1 = acc[ai][bj][m][1];
;                     if (ACT == 2) {
; #pragma unroll
;                         for (int e = 0; e < 4; ++e) { float a = fmaxf(v0[e], 0.f), b = fmaxf(v1[e], 0.f); v0[e] = a * a; v1[e] = b * b; } }
;                     u32x4 w; w.x = cvt_pk_bf16(v0[0], v0[1]); w.y = cvt_pk_bf16(v0[2], v0[3]); w.z = cvt_pk_bf16(v1[0], v1[1]); w.w = cvt_pk_bf16(v1[2], v1[3]);
;                     *(u32x4*)(rowp + bj * HALF) = w; } }
; template <class Epi, class Sched, bool ALIGN_EPI = false, bool SP2 = false>
; __device__ __forceinline__ void gemm_phase(PG8_LAS unsigned char* lds, const Gemm g, const Sched& S, const Epi& E) {
;     ...
;         if constexpr (!Epi::AFTER_DRAIN) { E(acc, cur, wr, wc, fr, fq); S.done(cur); }
;         if (!has_next) break;
; #pragma unroll
;         for (int a = 0; a < 2; ++a)
; #pragma unroll
;             for (int b = 0; b < 2; ++b)
; #pragma unroll
;                 for (int m = 0; m < 4; ++m)
; #pragma unroll
;                     for (int n = 0; n < 2; ++n) acc[a][b][m][n] = (f32x4){0.f, 0.f, 0.f, 0.f};
;         cur = nxt; cA = nA; cB = nB; ++ui;
;         if constexpr (ALIGN_EPI) { if (wr == 1) PG8_BAR; }
	v_cvt_pk_bf16_f32 v74, v78, v79
	v_cvt_pk_bf16_f32 v75, v80, v81
	v_cvt_pk_bf16_f32 v76, v84, v85
	v_cvt_pk_bf16_f32 v77, v86, v87
	v_max_f32_e32 v66, 0, v66
	v_max_f32_e32 v67, 0, v67
	global_store_dwordx4 v[82:83], v[74:77], off
	s_nop 1
	v_pk_mul_f32 v[74:75], v[66:67], v[66:67]
	v_max_f32_e32 v67, v68, v68
	v_max_f32_e32 v66, v72, v72
	v_max_f32_e32 v68, 0, v67
	v_max_f32_e32 v67, v73, v73
	v_max_f32_e32 v70, 0, v70
	v_max_f32_e32 v71, 0, v71
	v_max_f32_e32 v66, 0, v66
	v_max_f32_e32 v67, 0, v67
	v_max_f32_e32 v69, 0, v69
	v_pk_mul_f32 v[70:71], v[70:71], v[70:71]
	v_pk_mul_f32 v[72:73], v[66:67], v[66:67]
	v_pk_mul_f32 v[76:77], v[68:69], v[68:69]
	v_cvt_pk_bf16_f32 v66, v70, v71
	v_cvt_pk_bf16_f32 v67, v72, v73
	v_cvt_pk_bf16_f32 v68, v74, v75
	v_cvt_pk_bf16_f32 v69, v76, v77
	v_max_f32_e32 v58, 0, v58
	v_max_f32_e32 v59, 0, v59
	global_store_dwordx4 v[82:83], v[66:69], off offset:256
	s_nop 1
	v_pk_mul_f32 v[68:69], v[58:59], v[58:59]
	v_max_f32_e32 v59, v60, v60
	v_max_f32_e32 v62, 0, v62
	v_max_f32_e32 v63, 0, v63
	v_max_f32_e32 v58, v64, v64
	v_max_f32_e32 v60, 0, v59
	v_max_f32_e32 v59, v65, v65
	v_pk_mul_f32 v[62:63], v[62:63], v[62:63]
	v_max_f32_e32 v58, 0, v58
	v_max_f32_e32 v59, 0, v59
	v_max_f32_e32 v61, 0, v61
	s_mov_b32 s13, 0x100000
	v_pk_mul_f32 v[64:65], v[58:59], v[58:59]
	v_pk_mul_f32 v[70:71], v[60:61], v[60:61]
	v_cvt_pk_bf16_f32 v58, v62, v63
	v_add_co_u32_e32 v62, vcc, s13, v146
	v_cvt_pk_bf16_f32 v59, v64, v65
	v_cvt_pk_bf16_f32 v60, v68, v69
	v_cvt_pk_bf16_f32 v61, v70, v71
	v_addc_co_u32_e32 v63, vcc, 0, v147, vcc
	v_max_f32_e32 v50, 0, v50
	v_max_f32_e32 v51, 0, v51
	global_store_dwordx4 v[62:63], v[58:61], off
	s_nop 1
	v_pk_mul_f32 v[58:59], v[50:51], v[50:51]
	v_max_f32_e32 v51, v52, v52
	v_max_f32_e32 v50, v56, v56
	v_max_f32_e32 v52, 0, v51
	v_max_f32_e32 v51, v57, v57
	v_max_f32_e32 v54, 0, v54
	v_max_f32_e32 v55, 0, v55
	v_max_f32_e32 v50, 0, v50
	v_max_f32_e32 v51, 0, v51
	v_max_f32_e32 v53, 0, v53
	s_mov_b64 s[22:23], 0x100000
	v_pk_mul_f32 v[54:55], v[54:55], v[54:55]
	v_pk_mul_f32 v[56:57], v[50:51], v[50:51]
	v_pk_mul_f32 v[60:61], v[52:53], v[52:53]
	v_lshl_add_u64 v[66:67], v[146:147], 0, s[22:23]
	v_cvt_pk_bf16_f32 v50, v54, v55
	v_cvt_pk_bf16_f32 v51, v56, v57
	v_cvt_pk_bf16_f32 v52, v58, v59
	v_cvt_pk_bf16_f32 v53, v60, v61
	v_max_f32_e32 v42, 0, v42
	v_max_f32_e32 v43, 0, v43
	global_store_dwordx4 v[66:67], v[50:53], off offset:256
	s_nop 1
	v_pk_mul_f32 v[52:53], v[42:43], v[42:43]
	v_max_f32_e32 v43, v44, v44
	v_max_f32_e32 v46, 0, v46
	v_max_f32_e32 v47, 0, v47
	v_max_f32_e32 v42, v48, v48
	v_max_f32_e32 v44, 0, v43
	v_max_f32_e32 v43, v49, v49
	v_pk_mul_f32 v[46:47], v[46:47], v[46:47]
	v_max_f32_e32 v42, 0, v42
	v_max_f32_e32 v43, 0, v43
	v_max_f32_e32 v45, 0, v45
	s_mov_b32 s13, 0x120000
	v_pk_mul_f32 v[48:49], v[42:43], v[42:43]
	v_pk_mul_f32 v[54:55], v[44:45], v[44:45]
	v_cvt_pk_bf16_f32 v42, v46, v47
	v_add_co_u32_e32 v46, vcc, s13, v146
	v_cvt_pk_bf16_f32 v43, v48, v49
	v_cvt_pk_bf16_f32 v44, v52, v53
	v_cvt_pk_bf16_f32 v45, v54, v55
	v_addc_co_u32_e32 v47, vcc, 0, v147, vcc
	v_max_f32_e32 v34, 0, v34
	v_max_f32_e32 v35, 0, v35
	global_store_dwordx4 v[46:47], v[42:45], off
	s_nop 1
	v_pk_mul_f32 v[42:43], v[34:35], v[34:35]
	v_max_f32_e32 v35, v36, v36
	v_max_f32_e32 v34, v40, v40
	v_max_f32_e32 v36, 0, v35
	v_max_f32_e32 v35, v41, v41
	v_max_f32_e32 v38, 0, v38
	v_max_f32_e32 v39, 0, v39
	v_max_f32_e32 v34, 0, v34
	v_max_f32_e32 v35, 0, v35
	v_max_f32_e32 v37, 0, v37
	s_mov_b64 s[22:23], 0x120000
	v_pk_mul_f32 v[38:39], v[38:39], v[38:39]
	v_pk_mul_f32 v[40:41], v[34:35], v[34:35]
	v_pk_mul_f32 v[44:45], v[36:37], v[36:37]
	v_lshl_add_u64 v[50:51], v[146:147], 0, s[22:23]
	v_cvt_pk_bf16_f32 v34, v38, v39
	v_cvt_pk_bf16_f32 v35, v40, v41
	v_cvt_pk_bf16_f32 v36, v42, v43
	v_cvt_pk_bf16_f32 v37, v44, v45
	v_max_f32_e32 v26, 0, v26
	v_max_f32_e32 v27, 0, v27
	global_store_dwordx4 v[50:51], v[34:37], off offset:256
	s_nop 1
	v_pk_mul_f32 v[36:37], v[26:27], v[26:27]
	v_max_f32_e32 v27, v28, v28
	v_max_f32_e32 v30, 0, v30
	v_max_f32_e32 v31, 0, v31
	v_max_f32_e32 v26, v32, v32
	v_max_f32_e32 v28, 0, v27
	v_max_f32_e32 v27, v33, v33
	v_pk_mul_f32 v[30:31], v[30:31], v[30:31]
	v_max_f32_e32 v26, 0, v26
	v_max_f32_e32 v27, 0, v27
	v_max_f32_e32 v29, 0, v29
	s_mov_b32 s13, 0x140000
	v_pk_mul_f32 v[32:33], v[26:27], v[26:27]
	v_pk_mul_f32 v[38:39], v[28:29], v[28:29]
	v_cvt_pk_bf16_f32 v26, v30, v31
	v_add_co_u32_e32 v30, vcc, s13, v146
	v_cvt_pk_bf16_f32 v27, v32, v33
	v_cvt_pk_bf16_f32 v28, v36, v37
	v_cvt_pk_bf16_f32 v29, v38, v39
	v_addc_co_u32_e32 v31, vcc, 0, v147, vcc
	v_max_f32_e32 v18, 0, v18
	v_max_f32_e32 v19, 0, v19
	global_store_dwordx4 v[30:31], v[26:29], off
	s_nop 1
	v_pk_mul_f32 v[26:27], v[18:19], v[18:19]
	v_max_f32_e32 v19, v20, v20
	v_max_f32_e32 v18, v24, v24
	v_max_f32_e32 v20, 0, v19
	v_max_f32_e32 v19, v25, v25
	v_max_f32_e32 v22, 0, v22
	v_max_f32_e32 v23, 0, v23
	v_max_f32_e32 v18, 0, v18
	v_max_f32_e32 v19, 0, v19
	v_max_f32_e32 v21, 0, v21
	s_mov_b64 s[22:23], 0x140000
	v_pk_mul_f32 v[22:23], v[22:23], v[22:23]
	v_pk_mul_f32 v[24:25], v[18:19], v[18:19]
	v_pk_mul_f32 v[28:29], v[20:21], v[20:21]
	v_lshl_add_u64 v[34:35], v[146:147], 0, s[22:23]
	v_cvt_pk_bf16_f32 v18, v22, v23
	v_cvt_pk_bf16_f32 v19, v24, v25
	v_cvt_pk_bf16_f32 v20, v26, v27
	v_cvt_pk_bf16_f32 v21, v28, v29
	v_max_f32_e32 v10, 0, v10
	v_max_f32_e32 v11, 0, v11
	global_store_dwordx4 v[34:35], v[18:21], off offset:256
	s_nop 1
	v_pk_mul_f32 v[20:21], v[10:11], v[10:11]
	v_max_f32_e32 v11, v12, v12
	v_max_f32_e32 v14, 0, v14
	v_max_f32_e32 v15, 0, v15
	v_max_f32_e32 v10, v16, v16
	v_max_f32_e32 v12, 0, v11
	v_max_f32_e32 v11, v17, v17
	v_pk_mul_f32 v[14:15], v[14:15], v[14:15]
	v_max_f32_e32 v10, 0, v10
	v_max_f32_e32 v11, 0, v11
	v_max_f32_e32 v13, 0, v13
	s_mov_b32 s13, 0x160000
	v_pk_mul_f32 v[16:17], v[10:11], v[10:11]
	v_pk_mul_f32 v[22:23], v[12:13], v[12:13]
	v_cvt_pk_bf16_f32 v10, v14, v15
	v_add_co_u32_e32 v14, vcc, s13, v146
	v_cvt_pk_bf16_f32 v11, v16, v17
	v_cvt_pk_bf16_f32 v12, v20, v21
	v_cvt_pk_bf16_f32 v13, v22, v23
	v_addc_co_u32_e32 v15, vcc, 0, v147, vcc
	v_max_f32_e32 v2, 0, v2
	v_max_f32_e32 v3, 0, v3
	global_store_dwordx4 v[14:15], v[10:13], off
	s_nop 1
	v_pk_mul_f32 v[10:11], v[2:3], v[2:3]
	v_max_f32_e32 v3, v4, v4
	v_max_f32_e32 v2, v8, v8
	v_max_f32_e32 v4, 0, v3
	v_max_f32_e32 v3, v9, v9
	v_max_f32_e32 v6, 0, v6
	v_max_f32_e32 v7, 0, v7
	v_max_f32_e32 v2, 0, v2
	v_max_f32_e32 v3, 0, v3
	v_max_f32_e32 v5, 0, v5
	s_mov_b64 s[22:23], 0x160000
	v_pk_mul_f32 v[6:7], v[6:7], v[6:7]
	v_pk_mul_f32 v[8:9], v[2:3], v[2:3]
	v_pk_mul_f32 v[12:13], v[4:5], v[4:5]
	v_lshl_add_u64 v[18:19], v[146:147], 0, s[22:23]
	v_cvt_pk_bf16_f32 v2, v6, v7
	v_cvt_pk_bf16_f32 v3, v8, v9
	v_cvt_pk_bf16_f32 v4, v10, v11
	v_cvt_pk_bf16_f32 v5, v12, v13
	s_andn2_b64 vcc, exec, s[4:5]
	s_mov_b64 s[4:5], -1
	global_store_dwordx4 v[18:19], v[2:5], off offset:256
	s_cbranch_vccnz .LBB0_1015
	s_andn2_b64 vcc, exec, s[6:7]
	s_cbranch_vccnz .LBB0_1014
	s_barrier
	s_branch .LBB0_1014

;     __device__ __forceinline__ bool next(int i, Unit& u) const { const int L = i * G + c; if (L >= nunits) return false; const int t = L / S, ks = L % S; u.pm = pm0 + t / nN; u.pn = t % nN; u.ko = ks * Ksub; return true; }
; template <class Epi, class Sched, bool ALIGN_EPI = false, bool SP2 = false>
; __device__ __forceinline__ void gemm_phase(PG8_LAS unsigned char* lds, const Gemm g, const Sched& S, const Epi& E) {
;     ...
;         const bool has_next = S.next(ui + 1, nxt);
;         const char* nA = has_next ? (const char*)g.A + (size_t)nxt.pm * tstep + (size_t)nxt.ko * 2 : cA; const char* nB = has_next ? (const char*)g.Bt + (size_t)nxt.pn * tstep + (size_t)nxt.ko * 2 : cB;
;     ...
; #pragma unroll
;         for (int a = 0; a < 2; ++a)
; #pragma unroll
;             for (int b = 0; b < 2; ++b)
; #pragma unroll
;                 for (int m = 0; m < 4; ++m)
; #pragma unroll
;                     for (int n = 0; n < 2; ++n) acc[a][b][m][n] = (f32x4){0.f, 0.f, 0.f, 0.f};
.LBB0_1097:
	s_ashr_i32 s17, s16, 31
	s_lshl_b64 s[18:19], s[16:17], 21
	s_add_u32 s18, s62, s18
	s_addc_u32 s19, s63, s19
	s_and_b64 s[22:23], s[4:5], exec
	s_cselect_b32 s17, s19, s25
	s_cselect_b32 s40, s18, s24
	s_ashr_i32 s15, s14, 31
	s_lshl_b64 s[22:23], s[14:15], 21
	s_add_u32 s22, s59, s22
	s_addc_u32 s23, s64, s23
	s_and_b64 s[28:29], s[4:5], exec
	s_cselect_b32 s15, s23, s27
	s_cselect_b32 s41, s22, s26
	s_add_u32 s24, s24, 0x100080
	s_addc_u32 s25, s25, 0
	s_add_u32 s42, s26, 0x100
	v_mov_b32_e32 v2, 0
	s_addc_u32 s43, s27, 0
	s_mov_b32 s44, -2
	v_mov_b32_e32 v3, v2
	v_mov_b64_e32 v[4:5], 0
	v_mov_b64_e32 v[6:7], 0
	v_mov_b64_e32 v[8:9], 0
	v_mov_b64_e32 v[10:11], 0
	v_mov_b64_e32 v[12:13], 0
	v_mov_b64_e32 v[14:15], 0
	v_mov_b64_e32 v[16:17], 0
	v_mov_b64_e32 v[18:19], 0
	v_mov_b64_e32 v[20:21], 0
	v_mov_b64_e32 v[22:23], 0
	v_mov_b64_e32 v[24:25], 0
	v_mov_b64_e32 v[26:27], 0
	v_mov_b64_e32 v[28:29], 0
	v_mov_b64_e32 v[30:31], 0
	v_mov_b64_e32 v[32:33], 0
	v_mov_b64_e32 v[34:35], 0
	v_mov_b64_e32 v[36:37], 0
	v_mov_b64_e32 v[38:39], 0
	v_mov_b64_e32 v[40:41], 0
	v_mov_b64_e32 v[42:43], 0
	v_mov_b64_e32 v[44:45], 0
	v_mov_b64_e32 v[46:47], 0
	v_mov_b64_e32 v[48:49], 0
	v_mov_b64_e32 v[50:51], 0
	v_mov_b64_e32 v[52:53], 0
	v_mov_b64_e32 v[54:55], 0
	v_mov_b64_e32 v[56:57], 0
	v_mov_b64_e32 v[58:59], 0
	v_mov_b64_e32 v[60:61], 0
	v_mov_b64_e32 v[62:63], 0
	v_mov_b64_e32 v[64:65], 0
	v_mov_b64_e32 v[66:67], 0
	v_mov_b64_e32 v[68:69], 0
	v_mov_b64_e32 v[70:71], 0
	v_mov_b64_e32 v[72:73], 0
	v_mov_b64_e32 v[74:75], 0
	v_mov_b64_e32 v[76:77], 0
	v_mov_b64_e32 v[78:79], 0
	v_mov_b64_e32 v[80:81], 0
	v_mov_b64_e32 v[82:83], 0
	v_mov_b64_e32 v[84:85], 0
	v_mov_b64_e32 v[86:87], 0
	v_mov_b64_e32 v[88:89], 0
	v_mov_b64_e32 v[90:91], 0
	v_mov_b64_e32 v[92:93], 0
	v_mov_b64_e32 v[94:95], 0
	v_mov_b64_e32 v[96:97], 0
	v_mov_b64_e32 v[98:99], 0
	v_mov_b64_e32 v[100:101], 0
	v_mov_b64_e32 v[102:103], 0
	v_mov_b64_e32 v[104:105], 0
	v_mov_b64_e32 v[106:107], 0
	v_mov_b64_e32 v[108:109], 0
	v_mov_b64_e32 v[110:111], 0
	v_mov_b64_e32 v[112:113], 0
	v_mov_b64_e32 v[114:115], 0
	v_mov_b64_e32 v[116:117], 0
	v_mov_b64_e32 v[118:119], 0
	v_mov_b64_e32 v[120:121], 0
	v_mov_b64_e32 v[122:123], 0
	v_mov_b64_e32 v[124:125], 0
	v_mov_b64_e32 v[126:127], 0
	v_mov_b64_e32 v[128:129], 0

; template <class Epi, class Sched, bool ALIGN_EPI = false, bool SP2 = false>
; __device__ __forceinline__ void gemm_phase(PG8_LAS unsigned char* lds, const Gemm g, const Sched& S, const Epi& E) {
;     ...
; #pragma unroll
;         for (int a = 0; a < 2; ++a)
; #pragma unroll
;             for (int b = 0; b < 2; ++b)
; #pragma unroll
;                 for (int m = 0; m < 4; ++m)
; #pragma unroll
;                     for (int n = 0; n < 2; ++n) acc[a][b][m][n] = (f32x4){0.f, 0.f, 0.f, 0.f};
.LBB0_1117:
	s_add_u32 s28, s28, 0x100080
	s_addc_u32 s29, s29, 0
	s_add_u32 s7, s30, 0x100
	v_mov_b32_e32 v2, 0
	s_addc_u32 s19, s31, 0
	s_mov_b32 s21, -2
	v_mov_b32_e32 v3, v2
	v_mov_b64_e32 v[4:5], 0
	v_mov_b64_e32 v[6:7], 0
	v_mov_b64_e32 v[8:9], 0
	v_mov_b64_e32 v[10:11], 0
	v_mov_b64_e32 v[12:13], 0
	v_mov_b64_e32 v[14:15], 0
	v_mov_b64_e32 v[16:17], 0
	v_mov_b64_e32 v[18:19], 0
	v_mov_b64_e32 v[20:21], 0
	v_mov_b64_e32 v[22:23], 0
	v_mov_b64_e32 v[24:25], 0
	v_mov_b64_e32 v[26:27], 0
	v_mov_b64_e32 v[28:29], 0
	v_mov_b64_e32 v[30:31], 0
	v_mov_b64_e32 v[32:33], 0
	v_mov_b64_e32 v[34:35], 0
	v_mov_b64_e32 v[36:37], 0
	v_mov_b64_e32 v[38:39], 0
	v_mov_b64_e32 v[40:41], 0
	v_mov_b64_e32 v[42:43], 0
	v_mov_b64_e32 v[44:45], 0
	v_mov_b64_e32 v[46:47], 0
	v_mov_b64_e32 v[48:49], 0
	v_mov_b64_e32 v[50:51], 0
	v_mov_b64_e32 v[52:53], 0
	v_mov_b64_e32 v[54:55], 0
	v_mov_b64_e32 v[56:57], 0
	v_mov_b64_e32 v[58:59], 0
	v_mov_b64_e32 v[60:61], 0
	v_mov_b64_e32 v[62:63], 0
	v_mov_b64_e32 v[64:65], 0
	v_mov_b64_e32 v[66:67], 0
	v_mov_b64_e32 v[68:69], 0
	v_mov_b64_e32 v[70:71], 0
	v_mov_b64_e32 v[72:73], 0
	v_mov_b64_e32 v[74:75], 0
	v_mov_b64_e32 v[76:77], 0
	v_mov_b64_e32 v[78:79], 0
	v_mov_b64_e32 v[80:81], 0
	v_mov_b64_e32 v[82:83], 0
	v_mov_b64_e32 v[84:85], 0
	v_mov_b64_e32 v[86:87], 0
	v_mov_b64_e32 v[88:89], 0
	v_mov_b64_e32 v[90:91], 0
	v_mov_b64_e32 v[92:93], 0
	v_mov_b64_e32 v[94:95], 0
	v_mov_b64_e32 v[96:97], 0
	v_mov_b64_e32 v[98:99], 0
	v_mov_b64_e32 v[100:101], 0
	v_mov_b64_e32 v[102:103], 0
	v_mov_b64_e32 v[104:105], 0
	v_mov_b64_e32 v[106:107], 0
	v_mov_b64_e32 v[108:109], 0
	v_mov_b64_e32 v[110:111], 0
	v_mov_b64_e32 v[112:113], 0
	v_mov_b64_e32 v[114:115], 0
	v_mov_b64_e32 v[116:117], 0
	v_mov_b64_e32 v[118:119], 0
	v_mov_b64_e32 v[120:121], 0
	v_mov_b64_e32 v[122:123], 0
	v_mov_b64_e32 v[124:125], 0
	v_mov_b64_e32 v[126:127], 0
	v_mov_b64_e32 v[128:129], 0

;     __device__ __forceinline__ bool next(int i, Unit& u) const { const int L = i * G + c; if (L >= nunits) return false; const int t = L / S, ks = L % S; u.pm = pm0 + t / nN; u.pn = t % nN; u.ko = ks * Ksub; return true; }
; template <class Epi, class Sched, bool ALIGN_EPI = false, bool SP2 = false>
; __device__ __forceinline__ void gemm_phase(PG8_LAS unsigned char* lds, const Gemm g, const Sched& S, const Epi& E) {
;     ...
;         const bool has_next = S.next(ui + 1, nxt);
;         const char* nA = has_next ? (const char*)g.A + (size_t)nxt.pm * tstep + (size_t)nxt.ko * 2 : cA; const char* nB = has_next ? (const char*)g.Bt + (size_t)nxt.pn * tstep + (size_t)nxt.ko * 2 : cB;
;     ...
; #pragma unroll
;         for (int a = 0; a < 2; ++a)
; #pragma unroll
;             for (int b = 0; b < 2; ++b)
; #pragma unroll
;                 for (int m = 0; m < 4; ++m)
; #pragma unroll
;                     for (int n = 0; n < 2; ++n) acc[a][b][m][n] = (f32x4){0.f, 0.f, 0.f, 0.f};
.LBB0_1273:
	s_ashr_i32 s15, s14, 31
	s_lshl_b64 s[16:17], s[14:15], 19
	s_add_u32 s16, s68, s16
	s_addc_u32 s17, s69, s17
	s_and_b64 s[18:19], s[4:5], exec
	s_cselect_b32 s15, s17, s23
	s_cselect_b32 s42, s16, s22
	s_ashr_i32 s13, s12, 31
	s_lshl_b64 s[18:19], s[12:13], 19
	s_add_u32 s18, s60, s18
	s_addc_u32 s19, s61, s19
	s_and_b64 s[26:27], s[4:5], exec
	s_cselect_b32 s13, s19, s25
	s_cselect_b32 s43, s18, s24
	s_add_u32 s22, s22, 0x40080
	s_addc_u32 s23, s23, 0
	s_add_u32 s44, s24, 0x100
	v_mov_b32_e32 v2, 0
	s_addc_u32 s45, s25, 0
	s_mov_b32 s46, -2
	v_mov_b32_e32 v3, v2
	v_mov_b64_e32 v[4:5], 0
	v_mov_b64_e32 v[6:7], 0
	v_mov_b64_e32 v[8:9], 0
	v_mov_b64_e32 v[10:11], 0
	v_mov_b64_e32 v[12:13], 0
	v_mov_b64_e32 v[14:15], 0
	v_mov_b64_e32 v[16:17], 0
	v_mov_b64_e32 v[18:19], 0
	v_mov_b64_e32 v[20:21], 0
	v_mov_b64_e32 v[22:23], 0
	v_mov_b64_e32 v[24:25], 0
	v_mov_b64_e32 v[26:27], 0
	v_mov_b64_e32 v[28:29], 0
	v_mov_b64_e32 v[30:31], 0
	v_mov_b64_e32 v[32:33], 0
	v_mov_b64_e32 v[34:35], 0
	v_mov_b64_e32 v[36:37], 0
	v_mov_b64_e32 v[38:39], 0
	v_mov_b64_e32 v[40:41], 0
	v_mov_b64_e32 v[42:43], 0
	v_mov_b64_e32 v[44:45], 0
	v_mov_b64_e32 v[46:47], 0
	v_mov_b64_e32 v[48:49], 0
	v_mov_b64_e32 v[50:51], 0
	v_mov_b64_e32 v[52:53], 0
	v_mov_b64_e32 v[54:55], 0
	v_mov_b64_e32 v[56:57], 0
	v_mov_b64_e32 v[58:59], 0
	v_mov_b64_e32 v[60:61], 0
	v_mov_b64_e32 v[62:63], 0
	v_mov_b64_e32 v[64:65], 0
	v_mov_b64_e32 v[66:67], 0
	v_mov_b64_e32 v[68:69], 0
	v_mov_b64_e32 v[70:71], 0
	v_mov_b64_e32 v[72:73], 0
	v_mov_b64_e32 v[74:75], 0
	v_mov_b64_e32 v[76:77], 0
	v_mov_b64_e32 v[78:79], 0
	v_mov_b64_e32 v[80:81], 0
	v_mov_b64_e32 v[82:83], 0
	v_mov_b64_e32 v[84:85], 0
	v_mov_b64_e32 v[86:87], 0
	v_mov_b64_e32 v[88:89], 0
	v_mov_b64_e32 v[90:91], 0
	v_mov_b64_e32 v[92:93], 0
	v_mov_b64_e32 v[94:95], 0
	v_mov_b64_e32 v[96:97], 0
	v_mov_b64_e32 v[98:99], 0
	v_mov_b64_e32 v[100:101], 0
	v_mov_b64_e32 v[102:103], 0
	v_mov_b64_e32 v[104:105], 0
	v_mov_b64_e32 v[106:107], 0
	v_mov_b64_e32 v[108:109], 0
	v_mov_b64_e32 v[110:111], 0
	v_mov_b64_e32 v[112:113], 0
	v_mov_b64_e32 v[114:115], 0
	v_mov_b64_e32 v[116:117], 0
	v_mov_b64_e32 v[118:119], 0
	v_mov_b64_e32 v[120:121], 0
	v_mov_b64_e32 v[122:123], 0
	v_mov_b64_e32 v[124:125], 0
	v_mov_b64_e32 v[126:127], 0
	v_mov_b64_e32 v[128:129], 0

;     __device__ __forceinline__ bool next(int i, Unit& u) const { const int L = i * G + c; if (L >= nunits) return false; const int t = L / S, ks = L % S; u.pm = pm0 + t / nN; u.pn = t % nN; u.ko = ks * Ksub; return true; }
; template <class Epi, class Sched, bool ALIGN_EPI = false, bool SP2 = false>
; __device__ __forceinline__ void gemm_phase(PG8_LAS unsigned char* lds, const Gemm g, const Sched& S, const Epi& E) {
;     ...
;         const bool has_next = S.next(ui + 1, nxt);
;         const char* nA = has_next ? (const char*)g.A + (size_t)nxt.pm * tstep + (size_t)nxt.ko * 2 : cA; const char* nB = has_next ? (const char*)g.Bt + (size_t)nxt.pn * tstep + (size_t)nxt.ko * 2 : cB;
;     ...
; #pragma unroll
;         for (int a = 0; a < 2; ++a)
; #pragma unroll
;             for (int b = 0; b < 2; ++b)
; #pragma unroll
;                 for (int m = 0; m < 4; ++m)
; #pragma unroll
;                     for (int n = 0; n < 2; ++n) acc[a][b][m][n] = (f32x4){0.f, 0.f, 0.f, 0.f};
.LBB0_1447:
	s_ashr_i32 s25, s24, 31
	s_lshl_b64 s[26:27], s[24:25], 19
	s_mov_b64 s[28:29], s[92:93]
	s_add_u32 s26, s28, s26
	s_addc_u32 s27, s29, s27
	s_and_b64 s[28:29], s[4:5], exec
	s_cselect_b32 s25, s27, s35
	s_cselect_b32 s48, s26, s34
	s_ashr_i32 s23, s22, 31
	s_lshl_b64 s[28:29], s[22:23], 19
	v_readlane_b32 s38, v251, 53
	v_readlane_b32 s39, v251, 54
	s_add_u32 s28, s38, s28
	s_addc_u32 s29, s39, s29
	s_and_b64 s[38:39], s[4:5], exec
	s_cselect_b32 s23, s29, s37
	s_cselect_b32 s49, s28, s36
	s_add_u32 s34, s34, 0x40080
	s_addc_u32 s35, s35, 0
	s_add_u32 s50, s36, 0x100
	v_mov_b32_e32 v0, 0
	s_addc_u32 s51, s37, 0
	s_mov_b32 s52, -2
	v_mov_b32_e32 v1, v0
	v_mov_b64_e32 v[2:3], 0
	v_mov_b64_e32 v[4:5], 0
	v_mov_b64_e32 v[6:7], 0
	v_mov_b64_e32 v[8:9], 0
	v_mov_b64_e32 v[10:11], 0
	v_mov_b64_e32 v[12:13], 0
	v_mov_b64_e32 v[14:15], 0
	v_mov_b64_e32 v[16:17], 0
	v_mov_b64_e32 v[18:19], 0
	v_mov_b64_e32 v[20:21], 0
	v_mov_b64_e32 v[22:23], 0
	v_mov_b64_e32 v[24:25], 0
	v_mov_b64_e32 v[26:27], 0
	v_mov_b64_e32 v[28:29], 0
	v_mov_b64_e32 v[30:31], 0
	v_mov_b64_e32 v[32:33], 0
	v_mov_b64_e32 v[34:35], 0
	v_mov_b64_e32 v[36:37], 0
	v_mov_b64_e32 v[38:39], 0
	v_mov_b64_e32 v[40:41], 0
	v_mov_b64_e32 v[42:43], 0
	v_mov_b64_e32 v[44:45], 0
	v_mov_b64_e32 v[46:47], 0
	v_mov_b64_e32 v[48:49], 0
	v_mov_b64_e32 v[50:51], 0
	v_mov_b64_e32 v[52:53], 0
	v_mov_b64_e32 v[54:55], 0
	v_mov_b64_e32 v[56:57], 0
	v_mov_b64_e32 v[58:59], 0
	v_mov_b64_e32 v[60:61], 0
	v_mov_b64_e32 v[62:63], 0
	v_mov_b64_e32 v[64:65], 0
	v_mov_b64_e32 v[66:67], 0
	v_mov_b64_e32 v[68:69], 0
	v_mov_b64_e32 v[70:71], 0
	v_mov_b64_e32 v[72:73], 0
	v_mov_b64_e32 v[74:75], 0
	v_mov_b64_e32 v[76:77], 0
	v_mov_b64_e32 v[78:79], 0
	v_mov_b64_e32 v[80:81], 0
	v_mov_b64_e32 v[82:83], 0
	v_mov_b64_e32 v[84:85], 0
	v_mov_b64_e32 v[86:87], 0
	v_mov_b64_e32 v[88:89], 0
	v_mov_b64_e32 v[90:91], 0
	v_mov_b64_e32 v[92:93], 0
	v_mov_b64_e32 v[94:95], 0
	v_mov_b64_e32 v[96:97], 0
	v_mov_b64_e32 v[98:99], 0
	v_mov_b64_e32 v[100:101], 0
	v_mov_b64_e32 v[102:103], 0
	v_mov_b64_e32 v[104:105], 0
	v_mov_b64_e32 v[106:107], 0
	v_mov_b64_e32 v[108:109], 0
	v_mov_b64_e32 v[110:111], 0
	v_mov_b64_e32 v[112:113], 0
	v_mov_b64_e32 v[114:115], 0
	v_mov_b64_e32 v[116:117], 0
	v_mov_b64_e32 v[118:119], 0
	v_mov_b64_e32 v[120:121], 0
	v_mov_b64_e32 v[122:123], 0
	v_mov_b64_e32 v[124:125], 0
	v_mov_b64_e32 v[126:127], 0

; template <class Epi, class Sched, bool ALIGN_EPI = false, bool SP2 = false>
; __device__ __forceinline__ void gemm_phase(PG8_LAS unsigned char* lds, const Gemm g, const Sched& S, const Epi& E) {
;     ...
; #pragma unroll
;         for (int a = 0; a < 2; ++a)
; #pragma unroll
;             for (int b = 0; b < 2; ++b)
; #pragma unroll
;                 for (int m = 0; m < 4; ++m)
; #pragma unroll
;                     for (int n = 0; n < 2; ++n) acc[a][b][m][n] = (f32x4){0.f, 0.f, 0.f, 0.f};
.LBB0_1467:
	v_mov_b32_e32 v0, 0
	s_mov_b32 s7, 0
	s_mov_b64 s[34:35], -1
	s_mov_b64 s[36:37], 0
	v_mov_b32_e32 v1, v0
	v_mov_b64_e32 v[2:3], 0
	v_mov_b64_e32 v[4:5], 0
	v_mov_b64_e32 v[6:7], 0
	v_mov_b64_e32 v[8:9], 0
	v_mov_b64_e32 v[10:11], 0
	v_mov_b64_e32 v[12:13], 0
	v_mov_b64_e32 v[14:15], 0
	v_mov_b64_e32 v[16:17], 0
	v_mov_b64_e32 v[18:19], 0
	v_mov_b64_e32 v[20:21], 0
	v_mov_b64_e32 v[22:23], 0
	v_mov_b64_e32 v[24:25], 0
	v_mov_b64_e32 v[26:27], 0
	v_mov_b64_e32 v[28:29], 0
	v_mov_b64_e32 v[30:31], 0
	v_mov_b64_e32 v[32:33], 0
	v_mov_b64_e32 v[34:35], 0
	v_mov_b64_e32 v[36:37], 0
	v_mov_b64_e32 v[38:39], 0
	v_mov_b64_e32 v[40:41], 0
	v_mov_b64_e32 v[42:43], 0
	v_mov_b64_e32 v[44:45], 0
	v_mov_b64_e32 v[46:47], 0
	v_mov_b64_e32 v[48:49], 0
	v_mov_b64_e32 v[50:51], 0
	v_mov_b64_e32 v[52:53], 0
	v_mov_b64_e32 v[54:55], 0
	v_mov_b64_e32 v[56:57], 0
	v_mov_b64_e32 v[58:59], 0
	v_mov_b64_e32 v[60:61], 0
	v_mov_b64_e32 v[62:63], 0
	v_mov_b64_e32 v[64:65], 0
	v_mov_b64_e32 v[66:67], 0
	v_mov_b64_e32 v[68:69], 0
	v_mov_b64_e32 v[70:71], 0
	v_mov_b64_e32 v[72:73], 0
	v_mov_b64_e32 v[74:75], 0
	v_mov_b64_e32 v[76:77], 0
	v_mov_b64_e32 v[78:79], 0
	v_mov_b64_e32 v[80:81], 0
	v_mov_b64_e32 v[82:83], 0
	v_mov_b64_e32 v[84:85], 0
	v_mov_b64_e32 v[86:87], 0
	v_mov_b64_e32 v[88:89], 0
	v_mov_b64_e32 v[90:91], 0
	v_mov_b64_e32 v[92:93], 0
	v_mov_b64_e32 v[94:95], 0
	v_mov_b64_e32 v[96:97], 0
	v_mov_b64_e32 v[98:99], 0
	v_mov_b64_e32 v[100:101], 0
	v_mov_b64_e32 v[102:103], 0
	v_mov_b64_e32 v[104:105], 0
	v_mov_b64_e32 v[106:107], 0
	v_mov_b64_e32 v[108:109], 0
	v_mov_b64_e32 v[110:111], 0
	v_mov_b64_e32 v[112:113], 0
	v_mov_b64_e32 v[114:115], 0
	v_mov_b64_e32 v[116:117], 0
	v_mov_b64_e32 v[118:119], 0
	v_mov_b64_e32 v[120:121], 0
	v_mov_b64_e32 v[122:123], 0
	v_mov_b64_e32 v[124:125], 0
	v_mov_b64_e32 v[126:127], 0

;     __device__ __forceinline__ bool next(int i, Unit& u) const { const int L = i * G + c; if (L >= nunits) return false; const int t = L / S, ks = L % S; u.pm = pm0 + t / nN; u.pn = t % nN; u.ko = ks * Ksub; return true; }
; template <class Epi, class Sched, bool ALIGN_EPI = false, bool SP2 = false>
; __device__ __forceinline__ void gemm_phase(PG8_LAS unsigned char* lds, const Gemm g, const Sched& S, const Epi& E) {
;     ...
;         const bool has_next = S.next(ui + 1, nxt);
;         const char* nA = has_next ? (const char*)g.A + (size_t)nxt.pm * tstep + (size_t)nxt.ko * 2 : cA; const char* nB = has_next ? (const char*)g.Bt + (size_t)nxt.pn * tstep + (size_t)nxt.ko * 2 : cB;
;     ...
; #pragma unroll
;         for (int a = 0; a < 2; ++a)
; #pragma unroll
;             for (int b = 0; b < 2; ++b)
; #pragma unroll
;                 for (int m = 0; m < 4; ++m)
; #pragma unroll
;                     for (int n = 0; n < 2; ++n) acc[a][b][m][n] = (f32x4){0.f, 0.f, 0.f, 0.f};
.LBB0_1623:
	s_ashr_i32 s23, s22, 31
	s_lshl_b64 s[24:25], s[22:23], 19
	s_add_u32 s24, s68, s24
	s_addc_u32 s25, s69, s25
	s_and_b64 s[26:27], s[4:5], exec
	s_cselect_b32 s23, s25, s31
	s_cselect_b32 s54, s24, s30
	s_ashr_i32 s21, s20, 31
	s_lshl_b64 s[26:27], s[20:21], 19
	s_add_u32 s26, s2, s26
	s_addc_u32 s27, s3, s27
	s_and_b64 s[36:37], s[4:5], exec
	s_cselect_b32 s21, s27, s35
	s_cselect_b32 s55, s26, s34
	s_add_u32 s30, s30, 0x40080
	s_addc_u32 s31, s31, 0
	s_add_u32 s56, s34, 0x100
	v_mov_b32_e32 v0, 0
	s_addc_u32 s57, s35, 0
	s_mov_b32 s58, -2
	v_mov_b32_e32 v1, v0
	v_mov_b64_e32 v[2:3], 0
	v_mov_b64_e32 v[4:5], 0
	v_mov_b64_e32 v[6:7], 0
	v_mov_b64_e32 v[8:9], 0
	v_mov_b64_e32 v[10:11], 0
	v_mov_b64_e32 v[12:13], 0
	v_mov_b64_e32 v[14:15], 0
	v_mov_b64_e32 v[16:17], 0
	v_mov_b64_e32 v[18:19], 0
	v_mov_b64_e32 v[20:21], 0
	v_mov_b64_e32 v[22:23], 0
	v_mov_b64_e32 v[24:25], 0
	v_mov_b64_e32 v[26:27], 0
	v_mov_b64_e32 v[28:29], 0
	v_mov_b64_e32 v[30:31], 0
	v_mov_b64_e32 v[32:33], 0
	v_mov_b64_e32 v[34:35], 0
	v_mov_b64_e32 v[36:37], 0
	v_mov_b64_e32 v[38:39], 0
	v_mov_b64_e32 v[40:41], 0
	v_mov_b64_e32 v[42:43], 0
	v_mov_b64_e32 v[44:45], 0
	v_mov_b64_e32 v[46:47], 0
	v_mov_b64_e32 v[48:49], 0
	v_mov_b64_e32 v[50:51], 0
	v_mov_b64_e32 v[52:53], 0
	v_mov_b64_e32 v[54:55], 0
	v_mov_b64_e32 v[56:57], 0
	v_mov_b64_e32 v[58:59], 0
	v_mov_b64_e32 v[60:61], 0
	v_mov_b64_e32 v[62:63], 0
	v_mov_b64_e32 v[64:65], 0
	v_mov_b64_e32 v[66:67], 0
	v_mov_b64_e32 v[68:69], 0
	v_mov_b64_e32 v[70:71], 0
	v_mov_b64_e32 v[72:73], 0
	v_mov_b64_e32 v[74:75], 0
	v_mov_b64_e32 v[76:77], 0
	v_mov_b64_e32 v[78:79], 0
	v_mov_b64_e32 v[80:81], 0
	v_mov_b64_e32 v[82:83], 0
	v_mov_b64_e32 v[84:85], 0
	v_mov_b64_e32 v[86:87], 0
	v_mov_b64_e32 v[88:89], 0
	v_mov_b64_e32 v[90:91], 0
	v_mov_b64_e32 v[92:93], 0
	v_mov_b64_e32 v[94:95], 0
	v_mov_b64_e32 v[96:97], 0
	v_mov_b64_e32 v[98:99], 0
	v_mov_b64_e32 v[100:101], 0
	v_mov_b64_e32 v[102:103], 0
	v_mov_b64_e32 v[104:105], 0
	v_mov_b64_e32 v[106:107], 0
	v_mov_b64_e32 v[108:109], 0
	v_mov_b64_e32 v[110:111], 0
	v_mov_b64_e32 v[112:113], 0
	v_mov_b64_e32 v[114:115], 0
	v_mov_b64_e32 v[116:117], 0
	v_mov_b64_e32 v[118:119], 0
	v_mov_b64_e32 v[120:121], 0
	v_mov_b64_e32 v[122:123], 0
	v_mov_b64_e32 v[124:125], 0
	v_mov_b64_e32 v[126:127], 0

; __device__ __forceinline__ unsigned cvt_pk_bf16(float lo, float hi) { f32x2 v = {lo, hi}; bf16x2v b = __builtin_convertvector(v, bf16x2v); return __builtin_bit_cast(unsigned, b); }
;     __device__ __forceinline__ void operator()(const f32x4 (&acc)[2][2][4][2], const Unit& u, int wr, int wc, int fr, int fq) const {
;         const int row0 = u.pm * BM + wr * 64 + fr; const int col0 = u.pn * BM + wc * 32 + 8 * fq;
; #pragma unroll
;         for (int ai = 0; ai < 2; ++ai)
; #pragma unroll
;             for (int m = 0; m < 4; ++m) { bf16_t* rowp = O + (size_t)(row0 + ai * HALF + m * 16) * ldc + col0;
; #pragma unroll
;                 for (int bj = 0; bj < 2; ++bj) { f32x4 v0 = acc[ai][bj][m][0], v1 = acc[ai][bj][m][1];
;                     if (ACT == 2) {
; #pragma unroll
;                         for (int e = 0; e < 4; ++e) { float a = fmaxf(v0[e], 0.f), b = fmaxf(v1[e], 0.f); v0[e] = a * a; v1[e] = b * b; } }
;                     u32x4 w; w.x = cvt_pk_bf16(v0[0], v0[1]); w.y = cvt_pk_bf16(v0[2], v0[3]); w.z = cvt_pk_bf16(v1[0], v1[1]); w.w = cvt_pk_bf16(v1[2], v1[3]);
;                     *(u32x4*)(rowp + bj * HALF) = w; } }
.LBB0_1627:
	v_lshl_add_u32 v154, s28, 8, v146
	v_lshl_or_b32 v144, s53, 8, v147
	v_ashrrev_i32_e32 v155, 31, v154
	v_ashrrev_i32_e32 v145, 31, v144
	v_lshlrev_b64 v[156:157], 13, v[154:155]
	v_lshl_add_u64 v[156:157], s[62:63], 0, v[156:157]
	v_lshlrev_b64 v[158:159], 1, v[144:145]
	v_max_f32_e32 v120, 0, v120
	v_max_f32_e32 v121, 0, v121
	v_lshl_add_u64 v[144:145], v[156:157], 0, v[158:159]
	v_pk_mul_f32 v[156:157], v[120:121], v[120:121]
	v_max_f32_e32 v121, v122, v122
	v_max_f32_e32 v120, v126, v126
	v_max_f32_e32 v122, 0, v121
	v_max_f32_e32 v121, v127, v127
	v_max_f32_e32 v124, 0, v124
	v_max_f32_e32 v125, 0, v125
	v_max_f32_e32 v120, 0, v120
	v_max_f32_e32 v121, 0, v121
	v_max_f32_e32 v123, 0, v123
	v_pk_mul_f32 v[124:125], v[124:125], v[124:125]
	v_pk_mul_f32 v[126:127], v[120:121], v[120:121]
	v_pk_mul_f32 v[160:161], v[122:123], v[122:123]
	v_cvt_pk_bf16_f32 v120, v124, v125
	v_cvt_pk_bf16_f32 v121, v126, v127
	v_cvt_pk_bf16_f32 v122, v156, v157
	v_cvt_pk_bf16_f32 v123, v160, v161
	v_max_f32_e32 v112, 0, v112
	v_max_f32_e32 v113, 0, v113
	global_store_dwordx4 v[144:145], v[120:123], off
	s_nop 1
	v_pk_mul_f32 v[120:121], v[112:113], v[112:113]
	v_max_f32_e32 v113, v114, v114
	v_max_f32_e32 v112, v118, v118
	v_max_f32_e32 v114, 0, v113
	v_max_f32_e32 v113, v119, v119
	v_max_f32_e32 v116, 0, v116
	v_max_f32_e32 v117, 0, v117
	v_max_f32_e32 v112, 0, v112
	v_max_f32_e32 v113, 0, v113
	v_max_f32_e32 v115, 0, v115
	v_pk_mul_f32 v[116:117], v[116:117], v[116:117]
	v_pk_mul_f32 v[118:119], v[112:113], v[112:113]
	v_pk_mul_f32 v[122:123], v[114:115], v[114:115]
	v_cvt_pk_bf16_f32 v112, v116, v117
	v_cvt_pk_bf16_f32 v113, v118, v119
	v_cvt_pk_bf16_f32 v114, v120, v121
	v_cvt_pk_bf16_f32 v115, v122, v123
	v_max_f32_e32 v104, 0, v104
	v_max_f32_e32 v105, 0, v105
	global_store_dwordx4 v[144:145], v[112:115], off offset:256
	s_nop 1
	v_or_b32_e32 v112, 16, v154
	v_pk_mul_f32 v[114:115], v[104:105], v[104:105]
	v_max_f32_e32 v105, v106, v106
	v_ashrrev_i32_e32 v113, 31, v112
	v_max_f32_e32 v104, v110, v110
	v_max_f32_e32 v106, 0, v105
	v_max_f32_e32 v105, v111, v111
	v_lshlrev_b64 v[112:113], 13, v[112:113]
	v_max_f32_e32 v108, 0, v108
	v_max_f32_e32 v109, 0, v109
	v_max_f32_e32 v104, 0, v104
	v_max_f32_e32 v105, 0, v105
	v_max_f32_e32 v107, 0, v107
	v_lshl_add_u64 v[112:113], s[62:63], 0, v[112:113]
	v_pk_mul_f32 v[108:109], v[108:109], v[108:109]
	v_pk_mul_f32 v[110:111], v[104:105], v[104:105]
	v_pk_mul_f32 v[116:117], v[106:107], v[106:107]
	v_lshl_add_u64 v[112:113], v[112:113], 0, v[158:159]
	v_cvt_pk_bf16_f32 v104, v108, v109
	v_cvt_pk_bf16_f32 v105, v110, v111
	v_cvt_pk_bf16_f32 v106, v114, v115
	v_cvt_pk_bf16_f32 v107, v116, v117
	v_max_f32_e32 v96, 0, v96
	v_max_f32_e32 v97, 0, v97
	global_store_dwordx4 v[112:113], v[104:107], off
	s_nop 1
	v_pk_mul_f32 v[104:105], v[96:97], v[96:97]
	v_max_f32_e32 v97, v98, v98
	v_max_f32_e32 v96, v102, v102
	v_max_f32_e32 v98, 0, v97
	v_max_f32_e32 v97, v103, v103
	v_max_f32_e32 v100, 0, v100
	v_max_f32_e32 v101, 0, v101
	v_max_f32_e32 v96, 0, v96
	v_max_f32_e32 v97, 0, v97
	v_max_f32_e32 v99, 0, v99
	v_pk_mul_f32 v[100:101], v[100:101], v[100:101]
	v_pk_mul_f32 v[102:103], v[96:97], v[96:97]
	v_pk_mul_f32 v[106:107], v[98:99], v[98:99]
	v_cvt_pk_bf16_f32 v96, v100, v101
	v_cvt_pk_bf16_f32 v97, v102, v103
	v_cvt_pk_bf16_f32 v98, v104, v105
	v_cvt_pk_bf16_f32 v99, v106, v107
	v_max_f32_e32 v88, 0, v88
	v_max_f32_e32 v89, 0, v89
	global_store_dwordx4 v[112:113], v[96:99], off offset:256
	s_nop 1
	v_or_b32_e32 v96, 32, v154
	v_pk_mul_f32 v[98:99], v[88:89], v[88:89]
	v_max_f32_e32 v89, v90, v90
	v_ashrrev_i32_e32 v97, 31, v96
	v_max_f32_e32 v88, v94, v94
	v_max_f32_e32 v90, 0, v89
	v_max_f32_e32 v89, v95, v95
	v_lshlrev_b64 v[96:97], 13, v[96:97]
	v_max_f32_e32 v92, 0, v92
	v_max_f32_e32 v93, 0, v93
	v_max_f32_e32 v88, 0, v88
	v_max_f32_e32 v89, 0, v89
	v_max_f32_e32 v91, 0, v91
	v_lshl_add_u64 v[96:97], s[62:63], 0, v[96:97]
	v_pk_mul_f32 v[92:93], v[92:93], v[92:93]
	v_pk_mul_f32 v[94:95], v[88:89], v[88:89]
	v_pk_mul_f32 v[100:101], v[90:91], v[90:91]
	v_lshl_add_u64 v[96:97], v[96:97], 0, v[158:159]
	v_cvt_pk_bf16_f32 v88, v92, v93
	v_cvt_pk_bf16_f32 v89, v94, v95
	v_cvt_pk_bf16_f32 v90, v98, v99
	v_cvt_pk_bf16_f32 v91, v100, v101
	v_max_f32_e32 v80, 0, v80
	v_max_f32_e32 v81, 0, v81
	global_store_dwordx4 v[96:97], v[88:91], off
	s_nop 1
	v_pk_mul_f32 v[88:89], v[80:81], v[80:81]
	v_max_f32_e32 v81, v82, v82
	v_max_f32_e32 v80, v86, v86
	v_max_f32_e32 v82, 0, v81
	v_max_f32_e32 v81, v87, v87
	v_max_f32_e32 v84, 0, v84
	v_max_f32_e32 v85, 0, v85
	v_max_f32_e32 v80, 0, v80
	v_max_f32_e32 v81, 0, v81
	v_max_f32_e32 v83, 0, v83
	v_pk_mul_f32 v[84:85], v[84:85], v[84:85]
	v_pk_mul_f32 v[86:87], v[80:81], v[80:81]
	v_pk_mul_f32 v[90:91], v[82:83], v[82:83]
	v_cvt_pk_bf16_f32 v80, v84, v85
	v_cvt_pk_bf16_f32 v81, v86, v87
	v_cvt_pk_bf16_f32 v82, v88, v89
	v_cvt_pk_bf16_f32 v83, v90, v91
	v_max_f32_e32 v72, 0, v72
	v_max_f32_e32 v73, 0, v73
	global_store_dwordx4 v[96:97], v[80:83], off offset:256
	s_nop 1
	v_or_b32_e32 v80, 48, v154
	v_pk_mul_f32 v[82:83], v[72:73], v[72:73]
	v_max_f32_e32 v73, v74, v74
	v_ashrrev_i32_e32 v81, 31, v80
	v_max_f32_e32 v72, v78, v78
	v_max_f32_e32 v74, 0, v73
	v_max_f32_e32 v73, v79, v79
	v_lshlrev_b64 v[80:81], 13, v[80:81]
	v_max_f32_e32 v76, 0, v76
	v_max_f32_e32 v77, 0, v77
	v_max_f32_e32 v72, 0, v72
	v_max_f32_e32 v73, 0, v73
	v_max_f32_e32 v75, 0, v75
	v_lshl_add_u64 v[80:81], s[62:63], 0, v[80:81]
	v_pk_mul_f32 v[76:77], v[76:77], v[76:77]
	v_pk_mul_f32 v[78:79], v[72:73], v[72:73]
	v_pk_mul_f32 v[84:85], v[74:75], v[74:75]
	v_lshl_add_u64 v[80:81], v[80:81], 0, v[158:159]
; __device__ __forceinline__ unsigned cvt_pk_bf16(float lo, float hi) { f32x2 v = {lo, hi}; bf16x2v b = __builtin_convertvector(v, bf16x2v); return __builtin_bit_cast(unsigned, b); }
; #define PG8_BAR __builtin_amdgcn_s_barrier()
;     __device__ __forceinline__ void operator()(const f32x4 (&acc)[2][2][4][2], const Unit& u, int wr, int wc, int fr, int fq) const {
;         const int row0 = u.pm * BM + wr * 64 + fr; const int col0 = u.pn * BM + wc * 32 + 8 * fq;
; #pragma unroll
;         for (int ai = 0; ai < 2; ++ai)
; #pragma unroll
;             for (int m = 0; m < 4; ++m) { bf16_t* rowp = O + (size_t)(row0 + ai * HALF + m * 16) * ldc + col0;
; #pragma unroll
;                 for (int bj = 0; bj < 2; ++bj) { f32x4 v0 = acc[ai][bj][m][0], v1 = acc[ai][bj][m][1];
;                     if (ACT == 2) {
; #pragma unroll
;                         for (int e = 0; e < 4; ++e) { float a = fmaxf(v0[e], 0.f), b = fmaxf(v1[e], 0.f); v0[e] = a * a; v1[e] = b * b; } }
;                     u32x4 w; w.x = cvt_pk_bf16(v0[0], v0[1]); w.y = cvt_pk_bf16(v0[2], v0[3]); w.z = cvt_pk_bf16(v1[0], v1[1]); w.w = cvt_pk_bf16(v1[2], v1[3]);
;                     *(u32x4*)(rowp + bj * HALF) = w; } }
; template <class Epi, class Sched, bool ALIGN_EPI = false, bool SP2 = false>
; __device__ __forceinline__ void gemm_phase(PG8_LAS unsigned char* lds, const Gemm g, const Sched& S, const Epi& E) {
;     ...
;         if constexpr (!Epi::AFTER_DRAIN) { E(acc, cur, wr, wc, fr, fq); S.done(cur); }
;         if (!has_next) break;
; #pragma unroll
;         for (int a = 0; a < 2; ++a)
; #pragma unroll
;             for (int b = 0; b < 2; ++b)
; #pragma unroll
;                 for (int m = 0; m < 4; ++m)
; #pragma unroll
;                     for (int n = 0; n < 2; ++n) acc[a][b][m][n] = (f32x4){0.f, 0.f, 0.f, 0.f};
;         cur = nxt; cA = nA; cB = nB; ++ui;
;         if constexpr (ALIGN_EPI) { if (wr == 1) PG8_BAR; }
	v_cvt_pk_bf16_f32 v72, v76, v77
	v_cvt_pk_bf16_f32 v73, v78, v79
	v_cvt_pk_bf16_f32 v74, v82, v83
	v_cvt_pk_bf16_f32 v75, v84, v85
	v_max_f32_e32 v64, 0, v64
	v_max_f32_e32 v65, 0, v65
	global_store_dwordx4 v[80:81], v[72:75], off
	s_nop 1
	v_pk_mul_f32 v[72:73], v[64:65], v[64:65]
	v_max_f32_e32 v65, v66, v66
	v_max_f32_e32 v64, v70, v70
	v_max_f32_e32 v66, 0, v65
	v_max_f32_e32 v65, v71, v71
	v_max_f32_e32 v68, 0, v68
	v_max_f32_e32 v69, 0, v69
	v_max_f32_e32 v64, 0, v64
	v_max_f32_e32 v65, 0, v65
	v_max_f32_e32 v67, 0, v67
	v_pk_mul_f32 v[68:69], v[68:69], v[68:69]
	v_pk_mul_f32 v[70:71], v[64:65], v[64:65]
	v_pk_mul_f32 v[74:75], v[66:67], v[66:67]
	v_cvt_pk_bf16_f32 v64, v68, v69
	v_cvt_pk_bf16_f32 v65, v70, v71
	v_cvt_pk_bf16_f32 v66, v72, v73
	v_cvt_pk_bf16_f32 v67, v74, v75
	v_max_f32_e32 v56, 0, v56
	v_max_f32_e32 v57, 0, v57
	global_store_dwordx4 v[80:81], v[64:67], off offset:256
	s_nop 1
	v_pk_mul_f32 v[66:67], v[56:57], v[56:57]
	v_max_f32_e32 v57, v58, v58
	v_max_f32_e32 v60, 0, v60
	v_max_f32_e32 v61, 0, v61
	v_max_f32_e32 v56, v62, v62
	v_max_f32_e32 v58, 0, v57
	v_max_f32_e32 v57, v63, v63
	v_pk_mul_f32 v[60:61], v[60:61], v[60:61]
	v_max_f32_e32 v56, 0, v56
	v_max_f32_e32 v57, 0, v57
	v_max_f32_e32 v59, 0, v59
	v_pk_mul_f32 v[62:63], v[56:57], v[56:57]
	v_pk_mul_f32 v[68:69], v[58:59], v[58:59]
	v_cvt_pk_bf16_f32 v56, v60, v61
	v_add_co_u32_e32 v60, vcc, s47, v144
	v_cvt_pk_bf16_f32 v57, v62, v63
	v_cvt_pk_bf16_f32 v58, v66, v67
	v_cvt_pk_bf16_f32 v59, v68, v69
	v_addc_co_u32_e32 v61, vcc, 0, v145, vcc
	v_max_f32_e32 v48, 0, v48
	v_max_f32_e32 v49, 0, v49
	global_store_dwordx4 v[60:61], v[56:59], off
	s_nop 1
	v_pk_mul_f32 v[56:57], v[48:49], v[48:49]
	v_max_f32_e32 v49, v50, v50
	v_max_f32_e32 v48, v54, v54
	v_max_f32_e32 v50, 0, v49
	v_max_f32_e32 v49, v55, v55
	v_max_f32_e32 v52, 0, v52
	v_max_f32_e32 v53, 0, v53
	v_max_f32_e32 v48, 0, v48
	v_max_f32_e32 v49, 0, v49
	v_max_f32_e32 v51, 0, v51
	v_pk_mul_f32 v[52:53], v[52:53], v[52:53]
	v_pk_mul_f32 v[54:55], v[48:49], v[48:49]
	v_pk_mul_f32 v[58:59], v[50:51], v[50:51]
	v_lshl_add_u64 v[64:65], v[144:145], 0, s[12:13]
	v_cvt_pk_bf16_f32 v48, v52, v53
	v_cvt_pk_bf16_f32 v49, v54, v55
	v_cvt_pk_bf16_f32 v50, v56, v57
	v_cvt_pk_bf16_f32 v51, v58, v59
	v_max_f32_e32 v40, 0, v40
	v_max_f32_e32 v41, 0, v41
	global_store_dwordx4 v[64:65], v[48:51], off offset:256
	s_nop 1
	v_pk_mul_f32 v[50:51], v[40:41], v[40:41]
	v_max_f32_e32 v41, v42, v42
	v_max_f32_e32 v44, 0, v44
	v_max_f32_e32 v45, 0, v45
	v_max_f32_e32 v40, v46, v46
	v_max_f32_e32 v42, 0, v41
	v_max_f32_e32 v41, v47, v47
	v_pk_mul_f32 v[44:45], v[44:45], v[44:45]
	v_max_f32_e32 v40, 0, v40
	v_max_f32_e32 v41, 0, v41
	v_max_f32_e32 v43, 0, v43
	v_pk_mul_f32 v[46:47], v[40:41], v[40:41]
	v_pk_mul_f32 v[52:53], v[42:43], v[42:43]
	v_cvt_pk_bf16_f32 v40, v44, v45
	v_add_co_u32_e32 v44, vcc, s48, v144
	v_cvt_pk_bf16_f32 v41, v46, v47
	v_cvt_pk_bf16_f32 v42, v50, v51
	v_cvt_pk_bf16_f32 v43, v52, v53
	v_addc_co_u32_e32 v45, vcc, 0, v145, vcc
	v_max_f32_e32 v32, 0, v32
	v_max_f32_e32 v33, 0, v33
	global_store_dwordx4 v[44:45], v[40:43], off
	s_nop 1
	v_pk_mul_f32 v[40:41], v[32:33], v[32:33]
	v_max_f32_e32 v33, v34, v34
	v_max_f32_e32 v32, v38, v38
	v_max_f32_e32 v34, 0, v33
	v_max_f32_e32 v33, v39, v39
	v_max_f32_e32 v36, 0, v36
	v_max_f32_e32 v37, 0, v37
	v_max_f32_e32 v32, 0, v32
	v_max_f32_e32 v33, 0, v33
	v_max_f32_e32 v35, 0, v35
	v_pk_mul_f32 v[36:37], v[36:37], v[36:37]
	v_pk_mul_f32 v[38:39], v[32:33], v[32:33]
	v_pk_mul_f32 v[42:43], v[34:35], v[34:35]
	v_lshl_add_u64 v[48:49], v[144:145], 0, s[14:15]
	v_cvt_pk_bf16_f32 v32, v36, v37
	v_cvt_pk_bf16_f32 v33, v38, v39
	v_cvt_pk_bf16_f32 v34, v40, v41
	v_cvt_pk_bf16_f32 v35, v42, v43
	v_max_f32_e32 v24, 0, v24
	v_max_f32_e32 v25, 0, v25
	global_store_dwordx4 v[48:49], v[32:35], off offset:256
	s_nop 1
	v_pk_mul_f32 v[34:35], v[24:25], v[24:25]
	v_max_f32_e32 v25, v26, v26
	v_max_f32_e32 v28, 0, v28
	v_max_f32_e32 v29, 0, v29
	v_max_f32_e32 v24, v30, v30
	v_max_f32_e32 v26, 0, v25
	v_max_f32_e32 v25, v31, v31
	v_pk_mul_f32 v[28:29], v[28:29], v[28:29]
	v_max_f32_e32 v24, 0, v24
	v_max_f32_e32 v25, 0, v25
	v_max_f32_e32 v27, 0, v27
	v_pk_mul_f32 v[30:31], v[24:25], v[24:25]
	v_pk_mul_f32 v[36:37], v[26:27], v[26:27]
	v_cvt_pk_bf16_f32 v24, v28, v29
	v_add_co_u32_e32 v28, vcc, s49, v144
	v_cvt_pk_bf16_f32 v25, v30, v31
	v_cvt_pk_bf16_f32 v26, v34, v35
	v_cvt_pk_bf16_f32 v27, v36, v37
	v_addc_co_u32_e32 v29, vcc, 0, v145, vcc
	v_max_f32_e32 v16, 0, v16
	v_max_f32_e32 v17, 0, v17
	global_store_dwordx4 v[28:29], v[24:27], off
	s_nop 1
	v_pk_mul_f32 v[24:25], v[16:17], v[16:17]
	v_max_f32_e32 v17, v18, v18
	v_max_f32_e32 v16, v22, v22
	v_max_f32_e32 v18, 0, v17
	v_max_f32_e32 v17, v23, v23
	v_max_f32_e32 v20, 0, v20
	v_max_f32_e32 v21, 0, v21
	v_max_f32_e32 v16, 0, v16
	v_max_f32_e32 v17, 0, v17
	v_max_f32_e32 v19, 0, v19
	v_pk_mul_f32 v[20:21], v[20:21], v[20:21]
	v_pk_mul_f32 v[22:23], v[16:17], v[16:17]
	v_pk_mul_f32 v[26:27], v[18:19], v[18:19]
	v_lshl_add_u64 v[32:33], v[144:145], 0, s[16:17]
	v_cvt_pk_bf16_f32 v16, v20, v21
	v_cvt_pk_bf16_f32 v17, v22, v23
	v_cvt_pk_bf16_f32 v18, v24, v25
	v_cvt_pk_bf16_f32 v19, v26, v27
	v_max_f32_e32 v8, 0, v8
	v_max_f32_e32 v9, 0, v9
	global_store_dwordx4 v[32:33], v[16:19], off offset:256
	s_nop 1
	v_pk_mul_f32 v[18:19], v[8:9], v[8:9]
	v_max_f32_e32 v9, v10, v10
	v_max_f32_e32 v12, 0, v12
	v_max_f32_e32 v13, 0, v13
	v_max_f32_e32 v8, v14, v14
	v_max_f32_e32 v10, 0, v9
	v_max_f32_e32 v9, v15, v15
	v_pk_mul_f32 v[12:13], v[12:13], v[12:13]
	v_max_f32_e32 v8, 0, v8
	v_max_f32_e32 v9, 0, v9
	v_max_f32_e32 v11, 0, v11
	v_pk_mul_f32 v[14:15], v[8:9], v[8:9]
	v_pk_mul_f32 v[20:21], v[10:11], v[10:11]
	v_cvt_pk_bf16_f32 v8, v12, v13
	v_add_co_u32_e32 v12, vcc, s50, v144
	v_cvt_pk_bf16_f32 v9, v14, v15
	v_cvt_pk_bf16_f32 v10, v18, v19
	v_cvt_pk_bf16_f32 v11, v20, v21
	v_addc_co_u32_e32 v13, vcc, 0, v145, vcc
	v_max_f32_e32 v0, 0, v0
	v_max_f32_e32 v1, 0, v1
	global_store_dwordx4 v[12:13], v[8:11], off
	s_nop 1
	v_pk_mul_f32 v[8:9], v[0:1], v[0:1]
	v_max_f32_e32 v1, v2, v2
	v_max_f32_e32 v0, v6, v6
	v_max_f32_e32 v2, 0, v1
	v_max_f32_e32 v1, v7, v7
	v_max_f32_e32 v4, 0, v4
	v_max_f32_e32 v5, 0, v5
	v_max_f32_e32 v0, 0, v0
	v_max_f32_e32 v1, 0, v1
	v_max_f32_e32 v3, 0, v3
	v_pk_mul_f32 v[4:5], v[4:5], v[4:5]
	v_pk_mul_f32 v[6:7], v[0:1], v[0:1]
	v_pk_mul_f32 v[10:11], v[2:3], v[2:3]
	v_lshl_add_u64 v[16:17], v[144:145], 0, s[18:19]
	v_cvt_pk_bf16_f32 v0, v4, v5
	v_cvt_pk_bf16_f32 v1, v6, v7
	v_cvt_pk_bf16_f32 v2, v8, v9
	v_cvt_pk_bf16_f32 v3, v10, v11
	s_andn2_b64 vcc, exec, s[4:5]
	s_mov_b64 s[4:5], -1
	global_store_dwordx4 v[16:17], v[0:3], off offset:256
	s_cbranch_vccnz .LBB0_1620
	s_andn2_b64 vcc, exec, s[6:7]
	s_cbranch_vccnz .LBB0_1619
	s_barrier
	s_branch .LBB0_1619

;     __device__ __forceinline__ bool next(int i, Unit& u) const { const int L = i * G + c; if (L >= nunits) return false; const int t = L / S, ks = L % S; u.pm = pm0 + t / nN; u.pn = t % nN; u.ko = ks * Ksub; return true; }
; template <class Epi, class Sched, bool ALIGN_EPI = false, bool SP2 = false>
; __device__ __forceinline__ void gemm_phase(PG8_LAS unsigned char* lds, const Gemm g, const Sched& S, const Epi& E) {
;     ...
;         const bool has_next = S.next(ui + 1, nxt);
;         const char* nA = has_next ? (const char*)g.A + (size_t)nxt.pm * tstep + (size_t)nxt.ko * 2 : cA; const char* nB = has_next ? (const char*)g.Bt + (size_t)nxt.pn * tstep + (size_t)nxt.ko * 2 : cB;
;     ...
; #pragma unroll
;         for (int a = 0; a < 2; ++a)
; #pragma unroll
;             for (int b = 0; b < 2; ++b)
; #pragma unroll
;                 for (int m = 0; m < 4; ++m)
; #pragma unroll
;                     for (int n = 0; n < 2; ++n) acc[a][b][m][n] = (f32x4){0.f, 0.f, 0.f, 0.f};
.LBB0_1702:
	s_ashr_i32 s25, s24, 31
	s_lshl_b64 s[26:27], s[24:25], 21
	s_add_u32 s26, s62, s26
	s_addc_u32 s27, s63, s27
	s_and_b64 s[28:29], s[4:5], exec
	s_cselect_b32 s25, s27, s35
	s_cselect_b32 s50, s26, s34
	s_ashr_i32 s23, s22, 31
	s_lshl_b64 s[28:29], s[22:23], 21
	s_add_u32 s28, s2, s28
	s_addc_u32 s29, s3, s29
	s_and_b64 s[38:39], s[4:5], exec
	s_cselect_b32 s23, s29, s37
	s_cselect_b32 s51, s28, s36
	s_add_u32 s34, s34, 0x100080
	s_addc_u32 s35, s35, 0
	s_add_u32 s52, s36, 0x100
	v_mov_b32_e32 v0, 0
	s_addc_u32 s53, s37, 0
	s_mov_b32 s54, -2
	v_mov_b32_e32 v1, v0
	v_mov_b64_e32 v[2:3], 0
	v_mov_b64_e32 v[4:5], 0
	v_mov_b64_e32 v[6:7], 0
	v_mov_b64_e32 v[8:9], 0
	v_mov_b64_e32 v[10:11], 0
	v_mov_b64_e32 v[12:13], 0
	v_mov_b64_e32 v[14:15], 0
	v_mov_b64_e32 v[16:17], 0
	v_mov_b64_e32 v[18:19], 0
	v_mov_b64_e32 v[20:21], 0
	v_mov_b64_e32 v[22:23], 0
	v_mov_b64_e32 v[24:25], 0
	v_mov_b64_e32 v[26:27], 0
	v_mov_b64_e32 v[28:29], 0
	v_mov_b64_e32 v[30:31], 0
	v_mov_b64_e32 v[32:33], 0
	v_mov_b64_e32 v[34:35], 0
	v_mov_b64_e32 v[36:37], 0
	v_mov_b64_e32 v[38:39], 0
	v_mov_b64_e32 v[40:41], 0
	v_mov_b64_e32 v[42:43], 0
	v_mov_b64_e32 v[44:45], 0
	v_mov_b64_e32 v[46:47], 0
	v_mov_b64_e32 v[48:49], 0
	v_mov_b64_e32 v[50:51], 0
	v_mov_b64_e32 v[52:53], 0
	v_mov_b64_e32 v[54:55], 0
	v_mov_b64_e32 v[56:57], 0
	v_mov_b64_e32 v[58:59], 0
	v_mov_b64_e32 v[60:61], 0
	v_mov_b64_e32 v[62:63], 0
	v_mov_b64_e32 v[64:65], 0
	v_mov_b64_e32 v[66:67], 0
	v_mov_b64_e32 v[68:69], 0
	v_mov_b64_e32 v[70:71], 0
	v_mov_b64_e32 v[72:73], 0
	v_mov_b64_e32 v[74:75], 0
	v_mov_b64_e32 v[76:77], 0
	v_mov_b64_e32 v[78:79], 0
	v_mov_b64_e32 v[80:81], 0
	v_mov_b64_e32 v[82:83], 0
	v_mov_b64_e32 v[84:85], 0
	v_mov_b64_e32 v[86:87], 0
	v_mov_b64_e32 v[88:89], 0
	v_mov_b64_e32 v[90:91], 0
	v_mov_b64_e32 v[92:93], 0
	v_mov_b64_e32 v[94:95], 0
	v_mov_b64_e32 v[96:97], 0
	v_mov_b64_e32 v[98:99], 0
	v_mov_b64_e32 v[100:101], 0
	v_mov_b64_e32 v[102:103], 0
	v_mov_b64_e32 v[104:105], 0
	v_mov_b64_e32 v[106:107], 0
	v_mov_b64_e32 v[108:109], 0
	v_mov_b64_e32 v[110:111], 0
	v_mov_b64_e32 v[112:113], 0
	v_mov_b64_e32 v[114:115], 0
	v_mov_b64_e32 v[116:117], 0
	v_mov_b64_e32 v[118:119], 0
	v_mov_b64_e32 v[120:121], 0
	v_mov_b64_e32 v[122:123], 0
	v_mov_b64_e32 v[124:125], 0
	v_mov_b64_e32 v[126:127], 0

; template <class Epi, class Sched, bool ALIGN_EPI = false, bool SP2 = false>
; __device__ __forceinline__ void gemm_phase(PG8_LAS unsigned char* lds, const Gemm g, const Sched& S, const Epi& E) {
;     ...
; #pragma unroll
;         for (int a = 0; a < 2; ++a)
; #pragma unroll
;             for (int b = 0; b < 2; ++b)
; #pragma unroll
;                 for (int m = 0; m < 4; ++m)
; #pragma unroll
;                     for (int n = 0; n < 2; ++n) acc[a][b][m][n] = (f32x4){0.f, 0.f, 0.f, 0.f};
.LBB0_1722:
	s_add_u32 s30, s30, 0x100080
	s_addc_u32 s31, s31, 0
	s_add_u32 s7, s34, 0x100
	v_mov_b32_e32 v0, 0
	s_addc_u32 s21, s35, 0
	s_mov_b32 s23, -2
	v_mov_b32_e32 v1, v0
	v_mov_b64_e32 v[2:3], 0
	v_mov_b64_e32 v[4:5], 0
	v_mov_b64_e32 v[6:7], 0
	v_mov_b64_e32 v[8:9], 0
	v_mov_b64_e32 v[10:11], 0
	v_mov_b64_e32 v[12:13], 0
	v_mov_b64_e32 v[14:15], 0
	v_mov_b64_e32 v[16:17], 0
	v_mov_b64_e32 v[18:19], 0
	v_mov_b64_e32 v[20:21], 0
	v_mov_b64_e32 v[22:23], 0
	v_mov_b64_e32 v[24:25], 0
	v_mov_b64_e32 v[26:27], 0
	v_mov_b64_e32 v[28:29], 0
	v_mov_b64_e32 v[30:31], 0
	v_mov_b64_e32 v[32:33], 0
	v_mov_b64_e32 v[34:35], 0
	v_mov_b64_e32 v[36:37], 0
	v_mov_b64_e32 v[38:39], 0
	v_mov_b64_e32 v[40:41], 0
	v_mov_b64_e32 v[42:43], 0
	v_mov_b64_e32 v[44:45], 0
	v_mov_b64_e32 v[46:47], 0
	v_mov_b64_e32 v[48:49], 0
	v_mov_b64_e32 v[50:51], 0
	v_mov_b64_e32 v[52:53], 0
	v_mov_b64_e32 v[54:55], 0
	v_mov_b64_e32 v[56:57], 0
	v_mov_b64_e32 v[58:59], 0
	v_mov_b64_e32 v[60:61], 0
	v_mov_b64_e32 v[62:63], 0
	v_mov_b64_e32 v[64:65], 0
	v_mov_b64_e32 v[66:67], 0
	v_mov_b64_e32 v[68:69], 0
	v_mov_b64_e32 v[70:71], 0
	v_mov_b64_e32 v[72:73], 0
	v_mov_b64_e32 v[74:75], 0
	v_mov_b64_e32 v[76:77], 0
	v_mov_b64_e32 v[78:79], 0
	v_mov_b64_e32 v[80:81], 0
	v_mov_b64_e32 v[82:83], 0
	v_mov_b64_e32 v[84:85], 0
	v_mov_b64_e32 v[86:87], 0
	v_mov_b64_e32 v[88:89], 0
	v_mov_b64_e32 v[90:91], 0
	v_mov_b64_e32 v[92:93], 0
	v_mov_b64_e32 v[94:95], 0
	v_mov_b64_e32 v[96:97], 0
	v_mov_b64_e32 v[98:99], 0
	v_mov_b64_e32 v[100:101], 0
	v_mov_b64_e32 v[102:103], 0
	v_mov_b64_e32 v[104:105], 0
	v_mov_b64_e32 v[106:107], 0
	v_mov_b64_e32 v[108:109], 0
	v_mov_b64_e32 v[110:111], 0
	v_mov_b64_e32 v[112:113], 0
	v_mov_b64_e32 v[114:115], 0
	v_mov_b64_e32 v[116:117], 0
	v_mov_b64_e32 v[118:119], 0
	v_mov_b64_e32 v[120:121], 0
	v_mov_b64_e32 v[122:123], 0
	v_mov_b64_e32 v[124:125], 0
	v_mov_b64_e32 v[126:127], 0
